# norm phases (norm2, prep-with-add, prep layer0) software-pipelined: next trip loads issued before current math; reassociated sumsq
# baseline (speedup 1.0000x reference)
; __device__ __forceinline__ int BIDX() { int t = blockIdx.x; asm volatile("" : "+s"(t)); return t; }
; __device__ __forceinline__ float lo_bf(unsigned u) { return __uint_as_float(u << 16); }
; __device__ __forceinline__ float hi_bf(unsigned u) { return __uint_as_float(u & 0xffff0000u); }
; __device__ __forceinline__ void rmsnorm_rows_bf16(int swave, const float* xsrc, const bf16_t* add, float* xdst, const float* g, bf16_t* out) {
;   const int tidx = TIDX(swave);
;   const int bidx = BIDX();
;   const int wave = tidx >> 6, lane = tidx & 63;
;   float4 gg[4];
; #pragma unroll
;   for (int u = 0; u < 4; ++u) gg[u] = ((const float4*)g)[lane + 64 * u];
;   for (int row = (bidx * 8 + wave) * 2; row < TOK; row += gridDim.x * 16) {
;     const float4* xr = (const float4*)(xsrc + (size_t)row * DM);
;     float4 v[8]; float s0 = 0.f, s1 = 0.f;
; #pragma unroll
;     for (int u = 0; u < 8; ++u) { const f32x4 t = __builtin_nontemporal_load((const f32x4*)xr + lane + 64 * u); v[u] = make_float4(t[0], t[1], t[2], t[3]); }
;     if (add) {
;       const uint2* ar = (const uint2*)(add + (size_t)row * DM);
;       uint2 av[8];
; #pragma unroll
;       for (int u = 0; u < 8; ++u) av[u] = ar[lane + 64 * u];
; #pragma unroll
;       for (int u = 0; u < 8; ++u) { v[u].x += lo_bf(av[u].x); v[u].y += hi_bf(av[u].x); v[u].z += lo_bf(av[u].y); v[u].w += hi_bf(av[u].y); }
;       float4* xw = (float4*)(xdst + (size_t)row * DM);
; #pragma unroll
;       for (int u = 0; u < 8; ++u) { const f32x4 t = {v[u].x, v[u].y, v[u].z, v[u].w}; __builtin_nontemporal_store(t, (f32x4*)xw + lane + 64 * u); }
.LBB0_53:
	s_mov_b64 s[8:9], 0
	v_mov_b32_e32 v1, v147
	s_mov_b32 s2, s85
	v_ashrrev_i32_e32 v0, 5, v1
	v_and_b32_e32 v0, -2, v0
	v_lshl_add_u32 v0, s2, 4, v0
	s_mov_b32 s2, 0x8000
	v_cmp_gt_i32_e32 vcc, s2, v0
	s_and_saveexec_b64 s[2:3], vcc
	s_mov_b32 s12, 0x3a800000
	s_cbranch_execz .LBB0_56
	v_readlane_b32 s36, v248, 12
	s_lshl_b64 s[8:9], s[8:9], 2
	v_readlane_b32 s40, v248, 16
	v_readlane_b32 s41, v248, 17
	s_add_u32 s10, s40, s8
	s_addc_u32 s11, s41, s9
	v_readlane_b32 s8, v247, 49
	v_readlane_b32 s9, v247, 50
	s_mov_b32 s14, s8
	s_ashr_i32 s15, s8, 31
	v_writelane_b32 v247, s8, 49
	v_and_b32_e32 v1, 63, v1
	v_lshlrev_b32_e32 v2, 4, v1
	v_writelane_b32 v247, s9, 50
	s_lshl_b64 s[8:9], s[14:15], 12
	s_add_u32 s8, s10, s8
	s_addc_u32 s9, s11, s9
	global_load_dwordx4 v[4:7], v2, s[8:9]
	global_load_dwordx4 v[8:11], v2, s[8:9] offset:1024
	global_load_dwordx4 v[12:15], v2, s[8:9] offset:2048
	global_load_dwordx4 v[16:19], v2, s[8:9] offset:3072
	v_lshl_add_u64 v[24:25], s[6:7], 0, v[2:3]
	v_lshl_add_u64 v[26:27], s[4:5], 0, v[2:3]
	v_lshlrev_b32_e32 v2, 2, v1
	v_readlane_b32 s4, v247, 55
	v_xor_b32_e32 v36, 0x80, v2
	v_xor_b32_e32 v37, 64, v2
	v_xor_b32_e32 v38, 32, v2
	v_xor_b32_e32 v39, 16, v2
	v_xor_b32_e32 v40, 8, v2
	v_xor_b32_e32 v41, 4, v2
	v_lshlrev_b32_e32 v2, 3, v1
	v_readlane_b32 s5, v247, 56
	v_readlane_b32 s37, v248, 13
	v_readlane_b32 s38, v248, 14
	s_waitcnt vmcnt(0)
	v_lshl_add_u64 v[28:29], s[4:5], 0, v[2:3]
	s_mov_b64 s[4:5], 0xc000000
	v_lshl_add_u64 v[30:31], v[28:29], 0, s[4:5]
	s_mov_b64 s[4:5], 0
	v_readlane_b32 s39, v248, 15
	v_readlane_b32 s42, v248, 18
	v_readlane_b32 s43, v248, 19
	v_readlane_b32 s44, v248, 20
	v_readlane_b32 s45, v248, 21
	v_readlane_b32 s46, v248, 22
	v_readlane_b32 s47, v248, 23
	v_readlane_b32 s48, v248, 24
	v_readlane_b32 s49, v248, 25
	v_readlane_b32 s50, v248, 26
	v_readlane_b32 s51, v248, 27
	v_ashrrev_i32_e32 v209, 31, v0
	v_mov_b32_e32 v208, v0
	v_lshlrev_b64 v[210:211], 12, v[208:209]
	v_lshlrev_b64 v[208:209], 11, v[208:209]
	v_lshl_add_u64 v[208:209], v[30:31], 0, v[208:209]
	v_lshl_add_u64 v[210:211], v[24:25], 0, v[210:211]
	global_load_dwordx2 v[192:193], v[208:209], off
	global_load_dwordx2 v[194:195], v[208:209], off offset:512
	global_load_dwordx2 v[196:197], v[208:209], off offset:1024
	global_load_dwordx2 v[198:199], v[208:209], off offset:1536
	global_load_dwordx2 v[200:201], v[208:209], off offset:2048
	global_load_dwordx2 v[202:203], v[208:209], off offset:2560
	global_load_dwordx2 v[204:205], v[208:209], off offset:3072
	global_load_dwordx2 v[206:207], v[208:209], off offset:3584
	global_load_dwordx4 v[160:163], v[210:211], off nt
	global_load_dwordx4 v[164:167], v[210:211], off offset:1024 nt
	global_load_dwordx4 v[168:171], v[210:211], off offset:2048 nt
	global_load_dwordx4 v[172:175], v[210:211], off offset:3072 nt
	v_add_co_u32_e32 v210, vcc, 0x1000, v210
	s_nop 1
	v_addc_co_u32_e32 v211, vcc, 0, v211, vcc
	global_load_dwordx4 v[176:179], v[210:211], off nt
	global_load_dwordx4 v[180:183], v[210:211], off offset:1024 nt
	global_load_dwordx4 v[184:187], v[210:211], off offset:2048 nt
	global_load_dwordx4 v[188:191], v[210:211], off offset:3072 nt
	s_waitcnt vmcnt(0)
.LnA_loop:
	v_add_u32_e32 v216, s88, v0
	v_cmp_ge_i32_e32 vcc, s97, v216
	s_cbranch_vccz .LnA_nopf0
	v_ashrrev_i32_e32 v209, 31, v216
	v_mov_b32_e32 v208, v216
	v_lshlrev_b64 v[210:211], 12, v[208:209]
	v_lshlrev_b64 v[208:209], 11, v[208:209]
	v_lshl_add_u64 v[208:209], v[30:31], 0, v[208:209]
	v_lshl_add_u64 v[210:211], v[24:25], 0, v[210:211]
	global_load_dwordx2 v[96:97], v[208:209], off
	global_load_dwordx2 v[98:99], v[208:209], off offset:512
	global_load_dwordx2 v[100:101], v[208:209], off offset:1024
	global_load_dwordx2 v[102:103], v[208:209], off offset:1536
	global_load_dwordx2 v[104:105], v[208:209], off offset:2048
	global_load_dwordx2 v[106:107], v[208:209], off offset:2560
	global_load_dwordx2 v[108:109], v[208:209], off offset:3072
	global_load_dwordx2 v[110:111], v[208:209], off offset:3584
	global_load_dwordx4 v[64:67], v[210:211], off nt
	global_load_dwordx4 v[68:71], v[210:211], off offset:1024 nt
	global_load_dwordx4 v[72:75], v[210:211], off offset:2048 nt
	global_load_dwordx4 v[76:79], v[210:211], off offset:3072 nt
	v_add_co_u32_e32 v210, vcc, 0x1000, v210
	s_nop 1
	v_addc_co_u32_e32 v211, vcc, 0, v211, vcc
	global_load_dwordx4 v[80:83], v[210:211], off nt
	global_load_dwordx4 v[84:87], v[210:211], off offset:1024 nt
	global_load_dwordx4 v[88:91], v[210:211], off offset:2048 nt
	global_load_dwordx4 v[92:95], v[210:211], off offset:3072 nt
; __device__ __forceinline__ float lo_bf(unsigned u) { return __uint_as_float(u << 16); }
; __device__ __forceinline__ float hi_bf(unsigned u) { return __uint_as_float(u & 0xffff0000u); }
; __device__ __forceinline__ void rmsnorm_rows_bf16(int swave, const float* xsrc, const bf16_t* add, float* xdst, const float* g, bf16_t* out) {
;     ...
; #pragma unroll
;       for (int u = 0; u < 8; ++u) { v[u].x += lo_bf(av[u].x); v[u].y += hi_bf(av[u].x); v[u].z += lo_bf(av[u].y); v[u].w += hi_bf(av[u].y); }
;       float4* xw = (float4*)(xdst + (size_t)row * DM);
; #pragma unroll
;       for (int u = 0; u < 8; ++u) { const f32x4 t = {v[u].x, v[u].y, v[u].z, v[u].w}; __builtin_nontemporal_store(t, (f32x4*)xw + lane + 64 * u); }
;     }
; #pragma unroll
;     for (int u = 0; u < 4; ++u) {
;       s0 += v[u].x * v[u].x + v[u].y * v[u].y + v[u].z * v[u].z + v[u].w * v[u].w;
;       s1 += v[u + 4].x * v[u + 4].x + v[u + 4].y * v[u + 4].y + v[u + 4].z * v[u + 4].z + v[u + 4].w * v[u + 4].w;
;     }
; #pragma unroll
;     for (int o = 32; o > 0; o >>= 1) {
;       s0 += __int_as_float(__builtin_amdgcn_ds_bpermute((lane ^ o) << 2, __float_as_int(s0)));
;       s1 += __int_as_float(__builtin_amdgcn_ds_bpermute((lane ^ o) << 2, __float_as_int(s1)));
;     }
.LnA_nopf0:
	v_ashrrev_i32_e32 v1, 31, v0
	v_lshlrev_b64 v[212:213], 12, v[0:1]
	v_lshl_add_u64 v[212:213], v[26:27], 0, v[212:213]
	v_lshlrev_b64 v[214:215], 11, v[0:1]
	v_lshl_add_u64 v[214:215], v[28:29], 0, v[214:215]
	v_lshlrev_b32_e32 v112, 16, v192
	v_and_b32_e32 v113, 0xffff0000, v192
	v_lshlrev_b32_e32 v114, 16, v193
	v_and_b32_e32 v115, 0xffff0000, v193
	v_pk_add_f32 v[160:161], v[160:161], v[112:113]
	v_pk_add_f32 v[162:163], v[162:163], v[114:115]
	v_lshlrev_b32_e32 v116, 16, v194
	v_and_b32_e32 v117, 0xffff0000, v194
	v_lshlrev_b32_e32 v118, 16, v195
	v_and_b32_e32 v119, 0xffff0000, v195
	v_pk_add_f32 v[164:165], v[164:165], v[116:117]
	v_pk_add_f32 v[166:167], v[166:167], v[118:119]
	v_lshlrev_b32_e32 v120, 16, v196
	v_and_b32_e32 v121, 0xffff0000, v196
	v_lshlrev_b32_e32 v122, 16, v197
	v_and_b32_e32 v123, 0xffff0000, v197
	v_pk_add_f32 v[168:169], v[168:169], v[120:121]
	v_pk_add_f32 v[170:171], v[170:171], v[122:123]
	v_lshlrev_b32_e32 v124, 16, v198
	v_and_b32_e32 v125, 0xffff0000, v198
	v_lshlrev_b32_e32 v126, 16, v199
	v_and_b32_e32 v127, 0xffff0000, v199
	v_pk_add_f32 v[172:173], v[172:173], v[124:125]
	v_pk_add_f32 v[174:175], v[174:175], v[126:127]
	v_lshlrev_b32_e32 v112, 16, v200
	v_and_b32_e32 v113, 0xffff0000, v200
	v_lshlrev_b32_e32 v114, 16, v201
	v_and_b32_e32 v115, 0xffff0000, v201
	v_pk_add_f32 v[176:177], v[176:177], v[112:113]
	v_pk_add_f32 v[178:179], v[178:179], v[114:115]
	v_lshlrev_b32_e32 v116, 16, v202
	v_and_b32_e32 v117, 0xffff0000, v202
	v_lshlrev_b32_e32 v118, 16, v203
	v_and_b32_e32 v119, 0xffff0000, v203
	v_pk_add_f32 v[180:181], v[180:181], v[116:117]
	v_pk_add_f32 v[182:183], v[182:183], v[118:119]
	v_lshlrev_b32_e32 v120, 16, v204
	v_and_b32_e32 v121, 0xffff0000, v204
	v_lshlrev_b32_e32 v122, 16, v205
	v_and_b32_e32 v123, 0xffff0000, v205
	v_pk_add_f32 v[184:185], v[184:185], v[120:121]
	v_pk_add_f32 v[186:187], v[186:187], v[122:123]
	v_lshlrev_b32_e32 v124, 16, v206
	v_and_b32_e32 v125, 0xffff0000, v206
	v_lshlrev_b32_e32 v126, 16, v207
	v_and_b32_e32 v127, 0xffff0000, v207
	v_pk_add_f32 v[188:189], v[188:189], v[124:125]
	v_pk_add_f32 v[190:191], v[190:191], v[126:127]
	global_store_dwordx4 v[212:213], v[160:163], off nt
	global_store_dwordx4 v[212:213], v[164:167], off offset:1024 nt
	global_store_dwordx4 v[212:213], v[168:171], off offset:2048 nt
	global_store_dwordx4 v[212:213], v[172:175], off offset:3072 nt
	v_add_co_u32_e32 v212, vcc, 0x1000, v212
	s_nop 1
	v_addc_co_u32_e32 v213, vcc, 0, v213, vcc
	global_store_dwordx4 v[212:213], v[176:179], off nt
	global_store_dwordx4 v[212:213], v[180:183], off offset:1024 nt
	global_store_dwordx4 v[212:213], v[184:187], off offset:2048 nt
	global_store_dwordx4 v[212:213], v[188:191], off offset:3072 nt
	v_pk_mul_f32 v[128:129], v[160:161], v[160:161]
	v_pk_mul_f32 v[130:131], v[176:177], v[176:177]
	v_pk_fma_f32 v[128:129], v[162:163], v[162:163], v[128:129]
	v_pk_fma_f32 v[130:131], v[178:179], v[178:179], v[130:131]
	v_pk_fma_f32 v[128:129], v[164:165], v[164:165], v[128:129]
	v_pk_fma_f32 v[130:131], v[180:181], v[180:181], v[130:131]
	v_pk_fma_f32 v[128:129], v[166:167], v[166:167], v[128:129]
	v_pk_fma_f32 v[130:131], v[182:183], v[182:183], v[130:131]
	v_pk_fma_f32 v[128:129], v[168:169], v[168:169], v[128:129]
	v_pk_fma_f32 v[130:131], v[184:185], v[184:185], v[130:131]
	v_pk_fma_f32 v[128:129], v[170:171], v[170:171], v[128:129]
	v_pk_fma_f32 v[130:131], v[186:187], v[186:187], v[130:131]
	v_pk_fma_f32 v[128:129], v[172:173], v[172:173], v[128:129]
	v_pk_fma_f32 v[130:131], v[188:189], v[188:189], v[130:131]
	v_pk_fma_f32 v[128:129], v[174:175], v[174:175], v[128:129]
	v_pk_fma_f32 v[130:131], v[190:191], v[190:191], v[130:131]
	v_add_f32_e32 v218, v128, v129
	v_add_f32_e32 v219, v130, v131
	ds_bpermute_b32 v221, v36, v219
	ds_bpermute_b32 v220, v36, v218
	s_waitcnt lgkmcnt(0)
	v_pk_add_f32 v[218:219], v[218:219], v[220:221]
	ds_bpermute_b32 v221, v37, v219
	ds_bpermute_b32 v220, v37, v218
	s_waitcnt lgkmcnt(0)
	v_pk_add_f32 v[218:219], v[218:219], v[220:221]
	ds_bpermute_b32 v221, v38, v219
	ds_bpermute_b32 v220, v38, v218
	s_waitcnt lgkmcnt(0)
	v_pk_add_f32 v[218:219], v[218:219], v[220:221]
	ds_bpermute_b32 v221, v39, v219
	ds_bpermute_b32 v220, v39, v218
	s_waitcnt lgkmcnt(0)
	v_pk_add_f32 v[218:219], v[218:219], v[220:221]
	ds_bpermute_b32 v221, v40, v219
	ds_bpermute_b32 v220, v40, v218
	s_waitcnt lgkmcnt(0)
	v_pk_add_f32 v[218:219], v[218:219], v[220:221]
	ds_bpermute_b32 v221, v41, v219
	ds_bpermute_b32 v220, v41, v218
	s_waitcnt lgkmcnt(0)
; __device__ __forceinline__ unsigned pk2(float lo, float hi) { f32x2_t v = {lo, hi}; bf16x2_t b = __builtin_convertvector(v, bf16x2_t); return __builtin_bit_cast(unsigned, b); }
; __device__ __forceinline__ void rmsnorm_rows_bf16(int swave, const float* xsrc, const bf16_t* add, float* xdst, const float* g, bf16_t* out) {
;     ...
;     for (int o = 32; o > 0; o >>= 1) {
;       s0 += __int_as_float(__builtin_amdgcn_ds_bpermute((lane ^ o) << 2, __float_as_int(s0)));
;       s1 += __int_as_float(__builtin_amdgcn_ds_bpermute((lane ^ o) << 2, __float_as_int(s1)));
;     }
;     const float r0 = rsqrtf(s0 * (1.f / DM) + EPS), r1 = rsqrtf(s1 * (1.f / DM) + EPS);
; #pragma unroll
;     for (int u = 0; u < 8; ++u) {
;       const float r = u < 4 ? r0 : r1; const float4 g4 = gg[u & 3];
;       uint2 o; o.x = pk2(v[u].x * r * g4.x, v[u].y * r * g4.y); o.y = pk2(v[u].z * r * g4.z, v[u].w * r * g4.w);
;       *(uint2*)(out + (size_t)row * DM + (lane + 64 * u) * 4) = o;
;     }
	v_pk_add_f32 v[218:219], v[218:219], v[220:221]
	s_nop 0
	v_pk_fma_f32 v[218:219], v[218:219], s[12:13], v[132:133] op_sel_hi:[1,0,0]
	s_nop 0
	v_mul_f32_e32 v1, 0x4b800000, v218
	v_cmp_gt_f32_e32 vcc, s26, v218
	s_nop 1
	v_cndmask_b32_e32 v1, v218, v1, vcc
	v_rsq_f32_e32 v1, v1
	s_nop 0
	v_mul_f32_e32 v2, 0x45800000, v1
	v_cndmask_b32_e32 v222, v1, v2, vcc
	s_nop 0
	v_mul_f32_e32 v1, 0x4b800000, v219
	v_cmp_gt_f32_e32 vcc, s26, v219
	s_nop 1
	v_cndmask_b32_e32 v1, v219, v1, vcc
	v_rsq_f32_e32 v1, v1
	s_nop 0
	v_mul_f32_e32 v2, 0x45800000, v1
	v_cndmask_b32_e32 v224, v1, v2, vcc
	v_pk_mul_f32 v[112:113], v[160:161], v[222:223] op_sel_hi:[1,0]
	v_pk_mul_f32 v[114:115], v[162:163], v[222:223] op_sel_hi:[1,0]
	v_pk_mul_f32 v[112:113], v[4:5], v[112:113]
	v_pk_mul_f32 v[114:115], v[6:7], v[114:115]
	v_cvt_pk_bf16_f32 v226, v112, v113
	v_cvt_pk_bf16_f32 v227, v114, v115
	global_store_dwordx2 v[214:215], v[226:227], off
	v_pk_mul_f32 v[116:117], v[164:165], v[222:223] op_sel_hi:[1,0]
	v_pk_mul_f32 v[118:119], v[166:167], v[222:223] op_sel_hi:[1,0]
	v_pk_mul_f32 v[116:117], v[8:9], v[116:117]
	v_pk_mul_f32 v[118:119], v[10:11], v[118:119]
	v_cvt_pk_bf16_f32 v228, v116, v117
	v_cvt_pk_bf16_f32 v229, v118, v119
	global_store_dwordx2 v[214:215], v[228:229], off offset:512
	v_pk_mul_f32 v[120:121], v[168:169], v[222:223] op_sel_hi:[1,0]
	v_pk_mul_f32 v[122:123], v[170:171], v[222:223] op_sel_hi:[1,0]
	v_pk_mul_f32 v[120:121], v[12:13], v[120:121]
	v_pk_mul_f32 v[122:123], v[14:15], v[122:123]
	v_cvt_pk_bf16_f32 v230, v120, v121
	v_cvt_pk_bf16_f32 v231, v122, v123
	global_store_dwordx2 v[214:215], v[230:231], off offset:1024
	v_pk_mul_f32 v[124:125], v[172:173], v[222:223] op_sel_hi:[1,0]
	v_pk_mul_f32 v[126:127], v[174:175], v[222:223] op_sel_hi:[1,0]
	v_pk_mul_f32 v[124:125], v[16:17], v[124:125]
	v_pk_mul_f32 v[126:127], v[18:19], v[126:127]
	v_cvt_pk_bf16_f32 v232, v124, v125
	v_cvt_pk_bf16_f32 v233, v126, v127
	global_store_dwordx2 v[214:215], v[232:233], off offset:1536
	v_pk_mul_f32 v[112:113], v[176:177], v[224:225] op_sel_hi:[1,0]
	v_pk_mul_f32 v[114:115], v[178:179], v[224:225] op_sel_hi:[1,0]
	v_pk_mul_f32 v[112:113], v[4:5], v[112:113]
	v_pk_mul_f32 v[114:115], v[6:7], v[114:115]
	v_cvt_pk_bf16_f32 v226, v112, v113
	v_cvt_pk_bf16_f32 v227, v114, v115
	global_store_dwordx2 v[214:215], v[226:227], off offset:2048
	v_pk_mul_f32 v[116:117], v[180:181], v[224:225] op_sel_hi:[1,0]
	v_pk_mul_f32 v[118:119], v[182:183], v[224:225] op_sel_hi:[1,0]
	v_pk_mul_f32 v[116:117], v[8:9], v[116:117]
	v_pk_mul_f32 v[118:119], v[10:11], v[118:119]
	v_cvt_pk_bf16_f32 v228, v116, v117
	v_cvt_pk_bf16_f32 v229, v118, v119
	global_store_dwordx2 v[214:215], v[228:229], off offset:2560
	v_pk_mul_f32 v[120:121], v[184:185], v[224:225] op_sel_hi:[1,0]
	v_pk_mul_f32 v[122:123], v[186:187], v[224:225] op_sel_hi:[1,0]
	v_pk_mul_f32 v[120:121], v[12:13], v[120:121]
	v_pk_mul_f32 v[122:123], v[14:15], v[122:123]
	v_cvt_pk_bf16_f32 v230, v120, v121
	v_cvt_pk_bf16_f32 v231, v122, v123
	global_store_dwordx2 v[214:215], v[230:231], off offset:3072
	v_pk_mul_f32 v[124:125], v[188:189], v[224:225] op_sel_hi:[1,0]
	v_pk_mul_f32 v[126:127], v[190:191], v[224:225] op_sel_hi:[1,0]
	v_pk_mul_f32 v[124:125], v[16:17], v[124:125]
	v_pk_mul_f32 v[126:127], v[18:19], v[126:127]
	v_cvt_pk_bf16_f32 v232, v124, v125
	v_cvt_pk_bf16_f32 v233, v126, v127
	global_store_dwordx2 v[214:215], v[232:233], off offset:3584
	v_mov_b32_e32 v0, v216
	v_cmp_lt_i32_e32 vcc, s97, v0
	s_waitcnt vmcnt(16)
	s_or_b64 s[4:5], vcc, s[4:5]
	s_andn2_b64 exec, exec, s[4:5]
	s_cbranch_execz .LBB0_56
	v_add_u32_e32 v216, s88, v0
	v_cmp_ge_i32_e32 vcc, s97, v216
	s_cbranch_vccz .LnA_nopf1
	v_ashrrev_i32_e32 v209, 31, v216
	v_mov_b32_e32 v208, v216
	v_lshlrev_b64 v[210:211], 12, v[208:209]
	v_lshlrev_b64 v[208:209], 11, v[208:209]
	v_lshl_add_u64 v[208:209], v[30:31], 0, v[208:209]
	v_lshl_add_u64 v[210:211], v[24:25], 0, v[210:211]
	global_load_dwordx2 v[192:193], v[208:209], off
	global_load_dwordx2 v[194:195], v[208:209], off offset:512
	global_load_dwordx2 v[196:197], v[208:209], off offset:1024
	global_load_dwordx2 v[198:199], v[208:209], off offset:1536
	global_load_dwordx2 v[200:201], v[208:209], off offset:2048
	global_load_dwordx2 v[202:203], v[208:209], off offset:2560
	global_load_dwordx2 v[204:205], v[208:209], off offset:3072
	global_load_dwordx2 v[206:207], v[208:209], off offset:3584
	global_load_dwordx4 v[160:163], v[210:211], off nt
	global_load_dwordx4 v[164:167], v[210:211], off offset:1024 nt
	global_load_dwordx4 v[168:171], v[210:211], off offset:2048 nt
	global_load_dwordx4 v[172:175], v[210:211], off offset:3072 nt
	v_add_co_u32_e32 v210, vcc, 0x1000, v210
	s_nop 1
	v_addc_co_u32_e32 v211, vcc, 0, v211, vcc
	global_load_dwordx4 v[176:179], v[210:211], off nt
	global_load_dwordx4 v[180:183], v[210:211], off offset:1024 nt
	global_load_dwordx4 v[184:187], v[210:211], off offset:2048 nt
	global_load_dwordx4 v[188:191], v[210:211], off offset:3072 nt
; __device__ __forceinline__ float lo_bf(unsigned u) { return __uint_as_float(u << 16); }
; __device__ __forceinline__ float hi_bf(unsigned u) { return __uint_as_float(u & 0xffff0000u); }
; __device__ __forceinline__ void rmsnorm_rows_bf16(int swave, const float* xsrc, const bf16_t* add, float* xdst, const float* g, bf16_t* out) {
;     ...
; #pragma unroll
;       for (int u = 0; u < 8; ++u) { v[u].x += lo_bf(av[u].x); v[u].y += hi_bf(av[u].x); v[u].z += lo_bf(av[u].y); v[u].w += hi_bf(av[u].y); }
;       float4* xw = (float4*)(xdst + (size_t)row * DM);
; #pragma unroll
;       for (int u = 0; u < 8; ++u) { const f32x4 t = {v[u].x, v[u].y, v[u].z, v[u].w}; __builtin_nontemporal_store(t, (f32x4*)xw + lane + 64 * u); }
;     }
; #pragma unroll
;     for (int u = 0; u < 4; ++u) {
;       s0 += v[u].x * v[u].x + v[u].y * v[u].y + v[u].z * v[u].z + v[u].w * v[u].w;
;       s1 += v[u + 4].x * v[u + 4].x + v[u + 4].y * v[u + 4].y + v[u + 4].z * v[u + 4].z + v[u + 4].w * v[u + 4].w;
;     }
; #pragma unroll
;     for (int o = 32; o > 0; o >>= 1) {
;       s0 += __int_as_float(__builtin_amdgcn_ds_bpermute((lane ^ o) << 2, __float_as_int(s0)));
;       s1 += __int_as_float(__builtin_amdgcn_ds_bpermute((lane ^ o) << 2, __float_as_int(s1)));
;     }
.LnA_nopf1:
	v_ashrrev_i32_e32 v1, 31, v0
	v_lshlrev_b64 v[212:213], 12, v[0:1]
	v_lshl_add_u64 v[212:213], v[26:27], 0, v[212:213]
	v_lshlrev_b64 v[214:215], 11, v[0:1]
	v_lshl_add_u64 v[214:215], v[28:29], 0, v[214:215]
	v_lshlrev_b32_e32 v112, 16, v96
	v_and_b32_e32 v113, 0xffff0000, v96
	v_lshlrev_b32_e32 v114, 16, v97
	v_and_b32_e32 v115, 0xffff0000, v97
	v_pk_add_f32 v[64:65], v[64:65], v[112:113]
	v_pk_add_f32 v[66:67], v[66:67], v[114:115]
	v_lshlrev_b32_e32 v116, 16, v98
	v_and_b32_e32 v117, 0xffff0000, v98
	v_lshlrev_b32_e32 v118, 16, v99
	v_and_b32_e32 v119, 0xffff0000, v99
	v_pk_add_f32 v[68:69], v[68:69], v[116:117]
	v_pk_add_f32 v[70:71], v[70:71], v[118:119]
	v_lshlrev_b32_e32 v120, 16, v100
	v_and_b32_e32 v121, 0xffff0000, v100
	v_lshlrev_b32_e32 v122, 16, v101
	v_and_b32_e32 v123, 0xffff0000, v101
	v_pk_add_f32 v[72:73], v[72:73], v[120:121]
	v_pk_add_f32 v[74:75], v[74:75], v[122:123]
	v_lshlrev_b32_e32 v124, 16, v102
	v_and_b32_e32 v125, 0xffff0000, v102
	v_lshlrev_b32_e32 v126, 16, v103
	v_and_b32_e32 v127, 0xffff0000, v103
	v_pk_add_f32 v[76:77], v[76:77], v[124:125]
	v_pk_add_f32 v[78:79], v[78:79], v[126:127]
	v_lshlrev_b32_e32 v112, 16, v104
	v_and_b32_e32 v113, 0xffff0000, v104
	v_lshlrev_b32_e32 v114, 16, v105
	v_and_b32_e32 v115, 0xffff0000, v105
	v_pk_add_f32 v[80:81], v[80:81], v[112:113]
	v_pk_add_f32 v[82:83], v[82:83], v[114:115]
	v_lshlrev_b32_e32 v116, 16, v106
	v_and_b32_e32 v117, 0xffff0000, v106
	v_lshlrev_b32_e32 v118, 16, v107
	v_and_b32_e32 v119, 0xffff0000, v107
	v_pk_add_f32 v[84:85], v[84:85], v[116:117]
	v_pk_add_f32 v[86:87], v[86:87], v[118:119]
	v_lshlrev_b32_e32 v120, 16, v108
	v_and_b32_e32 v121, 0xffff0000, v108
	v_lshlrev_b32_e32 v122, 16, v109
	v_and_b32_e32 v123, 0xffff0000, v109
	v_pk_add_f32 v[88:89], v[88:89], v[120:121]
	v_pk_add_f32 v[90:91], v[90:91], v[122:123]
	v_lshlrev_b32_e32 v124, 16, v110
	v_and_b32_e32 v125, 0xffff0000, v110
	v_lshlrev_b32_e32 v126, 16, v111
	v_and_b32_e32 v127, 0xffff0000, v111
	v_pk_add_f32 v[92:93], v[92:93], v[124:125]
	v_pk_add_f32 v[94:95], v[94:95], v[126:127]
	global_store_dwordx4 v[212:213], v[64:67], off nt
	global_store_dwordx4 v[212:213], v[68:71], off offset:1024 nt
	global_store_dwordx4 v[212:213], v[72:75], off offset:2048 nt
	global_store_dwordx4 v[212:213], v[76:79], off offset:3072 nt
	v_add_co_u32_e32 v212, vcc, 0x1000, v212
	s_nop 1
	v_addc_co_u32_e32 v213, vcc, 0, v213, vcc
	global_store_dwordx4 v[212:213], v[80:83], off nt
	global_store_dwordx4 v[212:213], v[84:87], off offset:1024 nt
	global_store_dwordx4 v[212:213], v[88:91], off offset:2048 nt
	global_store_dwordx4 v[212:213], v[92:95], off offset:3072 nt
	v_pk_mul_f32 v[128:129], v[64:65], v[64:65]
	v_pk_mul_f32 v[130:131], v[80:81], v[80:81]
	v_pk_fma_f32 v[128:129], v[66:67], v[66:67], v[128:129]
	v_pk_fma_f32 v[130:131], v[82:83], v[82:83], v[130:131]
	v_pk_fma_f32 v[128:129], v[68:69], v[68:69], v[128:129]
	v_pk_fma_f32 v[130:131], v[84:85], v[84:85], v[130:131]
	v_pk_fma_f32 v[128:129], v[70:71], v[70:71], v[128:129]
	v_pk_fma_f32 v[130:131], v[86:87], v[86:87], v[130:131]
	v_pk_fma_f32 v[128:129], v[72:73], v[72:73], v[128:129]
	v_pk_fma_f32 v[130:131], v[88:89], v[88:89], v[130:131]
	v_pk_fma_f32 v[128:129], v[74:75], v[74:75], v[128:129]
	v_pk_fma_f32 v[130:131], v[90:91], v[90:91], v[130:131]
	v_pk_fma_f32 v[128:129], v[76:77], v[76:77], v[128:129]
	v_pk_fma_f32 v[130:131], v[92:93], v[92:93], v[130:131]
	v_pk_fma_f32 v[128:129], v[78:79], v[78:79], v[128:129]
	v_pk_fma_f32 v[130:131], v[94:95], v[94:95], v[130:131]
	v_add_f32_e32 v218, v128, v129
	v_add_f32_e32 v219, v130, v131
	ds_bpermute_b32 v221, v36, v219
	ds_bpermute_b32 v220, v36, v218
	s_waitcnt lgkmcnt(0)
	v_pk_add_f32 v[218:219], v[218:219], v[220:221]
	ds_bpermute_b32 v221, v37, v219
	ds_bpermute_b32 v220, v37, v218
	s_waitcnt lgkmcnt(0)
	v_pk_add_f32 v[218:219], v[218:219], v[220:221]
	ds_bpermute_b32 v221, v38, v219
	ds_bpermute_b32 v220, v38, v218
	s_waitcnt lgkmcnt(0)
; __device__ __forceinline__ unsigned pk2(float lo, float hi) { f32x2_t v = {lo, hi}; bf16x2_t b = __builtin_convertvector(v, bf16x2_t); return __builtin_bit_cast(unsigned, b); }
; __device__ __forceinline__ void rmsnorm_rows_bf16(int swave, const float* xsrc, const bf16_t* add, float* xdst, const float* g, bf16_t* out) {
;     ...
;     for (int o = 32; o > 0; o >>= 1) {
;       s0 += __int_as_float(__builtin_amdgcn_ds_bpermute((lane ^ o) << 2, __float_as_int(s0)));
;       s1 += __int_as_float(__builtin_amdgcn_ds_bpermute((lane ^ o) << 2, __float_as_int(s1)));
;     }
;     const float r0 = rsqrtf(s0 * (1.f / DM) + EPS), r1 = rsqrtf(s1 * (1.f / DM) + EPS);
; #pragma unroll
;     for (int u = 0; u < 8; ++u) {
;       const float r = u < 4 ? r0 : r1; const float4 g4 = gg[u & 3];
;       uint2 o; o.x = pk2(v[u].x * r * g4.x, v[u].y * r * g4.y); o.y = pk2(v[u].z * r * g4.z, v[u].w * r * g4.w);
;       *(uint2*)(out + (size_t)row * DM + (lane + 64 * u) * 4) = o;
;     }
	v_pk_add_f32 v[218:219], v[218:219], v[220:221]
	ds_bpermute_b32 v221, v39, v219
	ds_bpermute_b32 v220, v39, v218
	s_waitcnt lgkmcnt(0)
	v_pk_add_f32 v[218:219], v[218:219], v[220:221]
	ds_bpermute_b32 v221, v40, v219
	ds_bpermute_b32 v220, v40, v218
	s_waitcnt lgkmcnt(0)
	v_pk_add_f32 v[218:219], v[218:219], v[220:221]
	ds_bpermute_b32 v221, v41, v219
	ds_bpermute_b32 v220, v41, v218
	s_waitcnt lgkmcnt(0)
	v_pk_add_f32 v[218:219], v[218:219], v[220:221]
	s_nop 0
	v_pk_fma_f32 v[218:219], v[218:219], s[12:13], v[132:133] op_sel_hi:[1,0,0]
	s_nop 0
	v_mul_f32_e32 v1, 0x4b800000, v218
	v_cmp_gt_f32_e32 vcc, s26, v218
	s_nop 1
	v_cndmask_b32_e32 v1, v218, v1, vcc
	v_rsq_f32_e32 v1, v1
	s_nop 0
	v_mul_f32_e32 v2, 0x45800000, v1
	v_cndmask_b32_e32 v222, v1, v2, vcc
	s_nop 0
	v_mul_f32_e32 v1, 0x4b800000, v219
	v_cmp_gt_f32_e32 vcc, s26, v219
	s_nop 1
	v_cndmask_b32_e32 v1, v219, v1, vcc
	v_rsq_f32_e32 v1, v1
	s_nop 0
	v_mul_f32_e32 v2, 0x45800000, v1
	v_cndmask_b32_e32 v224, v1, v2, vcc
	v_pk_mul_f32 v[112:113], v[64:65], v[222:223] op_sel_hi:[1,0]
	v_pk_mul_f32 v[114:115], v[66:67], v[222:223] op_sel_hi:[1,0]
	v_pk_mul_f32 v[112:113], v[4:5], v[112:113]
	v_pk_mul_f32 v[114:115], v[6:7], v[114:115]
	v_cvt_pk_bf16_f32 v226, v112, v113
	v_cvt_pk_bf16_f32 v227, v114, v115
	global_store_dwordx2 v[214:215], v[226:227], off
	v_pk_mul_f32 v[116:117], v[68:69], v[222:223] op_sel_hi:[1,0]
	v_pk_mul_f32 v[118:119], v[70:71], v[222:223] op_sel_hi:[1,0]
	v_pk_mul_f32 v[116:117], v[8:9], v[116:117]
	v_pk_mul_f32 v[118:119], v[10:11], v[118:119]
	v_cvt_pk_bf16_f32 v228, v116, v117
	v_cvt_pk_bf16_f32 v229, v118, v119
	global_store_dwordx2 v[214:215], v[228:229], off offset:512
	v_pk_mul_f32 v[120:121], v[72:73], v[222:223] op_sel_hi:[1,0]
	v_pk_mul_f32 v[122:123], v[74:75], v[222:223] op_sel_hi:[1,0]
	v_pk_mul_f32 v[120:121], v[12:13], v[120:121]
	v_pk_mul_f32 v[122:123], v[14:15], v[122:123]
	v_cvt_pk_bf16_f32 v230, v120, v121
	v_cvt_pk_bf16_f32 v231, v122, v123
	global_store_dwordx2 v[214:215], v[230:231], off offset:1024
	v_pk_mul_f32 v[124:125], v[76:77], v[222:223] op_sel_hi:[1,0]
	v_pk_mul_f32 v[126:127], v[78:79], v[222:223] op_sel_hi:[1,0]
	v_pk_mul_f32 v[124:125], v[16:17], v[124:125]
	v_pk_mul_f32 v[126:127], v[18:19], v[126:127]
	v_cvt_pk_bf16_f32 v232, v124, v125
	v_cvt_pk_bf16_f32 v233, v126, v127
	global_store_dwordx2 v[214:215], v[232:233], off offset:1536
	v_pk_mul_f32 v[112:113], v[80:81], v[224:225] op_sel_hi:[1,0]
	v_pk_mul_f32 v[114:115], v[82:83], v[224:225] op_sel_hi:[1,0]
	v_pk_mul_f32 v[112:113], v[4:5], v[112:113]
	v_pk_mul_f32 v[114:115], v[6:7], v[114:115]
	v_cvt_pk_bf16_f32 v226, v112, v113
	v_cvt_pk_bf16_f32 v227, v114, v115
	global_store_dwordx2 v[214:215], v[226:227], off offset:2048
	v_pk_mul_f32 v[116:117], v[84:85], v[224:225] op_sel_hi:[1,0]
	v_pk_mul_f32 v[118:119], v[86:87], v[224:225] op_sel_hi:[1,0]
	v_pk_mul_f32 v[116:117], v[8:9], v[116:117]
	v_pk_mul_f32 v[118:119], v[10:11], v[118:119]
	v_cvt_pk_bf16_f32 v228, v116, v117
	v_cvt_pk_bf16_f32 v229, v118, v119
	global_store_dwordx2 v[214:215], v[228:229], off offset:2560
	v_pk_mul_f32 v[120:121], v[88:89], v[224:225] op_sel_hi:[1,0]
	v_pk_mul_f32 v[122:123], v[90:91], v[224:225] op_sel_hi:[1,0]
	v_pk_mul_f32 v[120:121], v[12:13], v[120:121]
	v_pk_mul_f32 v[122:123], v[14:15], v[122:123]
	v_cvt_pk_bf16_f32 v230, v120, v121
	v_cvt_pk_bf16_f32 v231, v122, v123
	global_store_dwordx2 v[214:215], v[230:231], off offset:3072
	v_pk_mul_f32 v[124:125], v[92:93], v[224:225] op_sel_hi:[1,0]
	v_pk_mul_f32 v[126:127], v[94:95], v[224:225] op_sel_hi:[1,0]
	v_pk_mul_f32 v[124:125], v[16:17], v[124:125]
	v_pk_mul_f32 v[126:127], v[18:19], v[126:127]
	v_cvt_pk_bf16_f32 v232, v124, v125
	v_cvt_pk_bf16_f32 v233, v126, v127
	global_store_dwordx2 v[214:215], v[232:233], off offset:3584
	v_mov_b32_e32 v0, v216
	v_cmp_lt_i32_e32 vcc, s97, v0
	s_waitcnt vmcnt(16)
	s_or_b64 s[4:5], vcc, s[4:5]
	s_andn2_b64 exec, exec, s[4:5]
	s_cbranch_execnz .LnA_loop

; __device__ __forceinline__ int BIDX() { int t = blockIdx.x; asm volatile("" : "+s"(t)); return t; }
; __device__ __forceinline__ const float* INP(const Params& p, int k) { return p.in[k] + opaque0(); }
; __device__ __forceinline__ char* WS(const Params& p) { return p.ws + opaque0(); }
; __device__ __forceinline__ float* OUTP(const Params& p) { return p.out + opaque0(); }
; __device__ __forceinline__ float lo_bf(unsigned u) { return __uint_as_float(u << 16); }
; __device__ __forceinline__ float hi_bf(unsigned u) { return __uint_as_float(u & 0xffff0000u); }
; __device__ __forceinline__ void rmsnorm_rows_bf16(int swave, const float* xsrc, const bf16_t* add, float* xdst, const float* g, bf16_t* out) {
;   const int tidx = TIDX(swave);
;   const int bidx = BIDX();
;   const int wave = tidx >> 6, lane = tidx & 63;
;   float4 gg[4];
; #pragma unroll
;   for (int u = 0; u < 4; ++u) gg[u] = ((const float4*)g)[lane + 64 * u];
;   for (int row = (bidx * 8 + wave) * 2; row < TOK; row += gridDim.x * 16) {
;     const float4* xr = (const float4*)(xsrc + (size_t)row * DM);
;     float4 v[8]; float s0 = 0.f, s1 = 0.f;
; #pragma unroll
;     for (int u = 0; u < 8; ++u) { const f32x4 t = __builtin_nontemporal_load((const f32x4*)xr + lane + 64 * u); v[u] = make_float4(t[0], t[1], t[2], t[3]); }
;     if (add) {
;       const uint2* ar = (const uint2*)(add + (size_t)row * DM);
;       uint2 av[8];
; #pragma unroll
;       for (int u = 0; u < 8; ++u) av[u] = ar[lane + 64 * u];
; #pragma unroll
;       for (int u = 0; u < 8; ++u) { v[u].x += lo_bf(av[u].x); v[u].y += hi_bf(av[u].x); v[u].z += lo_bf(av[u].y); v[u].w += hi_bf(av[u].y); }
;       float4* xw = (float4*)(xdst + (size_t)row * DM);
; #pragma unroll
;       for (int u = 0; u < 8; ++u) { const f32x4 t = {v[u].x, v[u].y, v[u].z, v[u].w}; __builtin_nontemporal_store(t, (f32x4*)xw + lane + 64 * u); }
; __device__ void prep_phase(int swave, const Params& p, int layer, char* shm) {
;     ...
;   if (layer == 0) rmsnorm_rows_bf16(swave, INP(p, 0), nullptr, nullptr, INP(p, 1), (bf16_t*)(WS(p) + OFF_A16));
;   else { float* o = OUTP(p); rmsnorm_rows_bf16(swave, o, (const bf16_t*)(WS(p) + OFF_PU), o, INP(p, 1) + (size_t)layer * DM, (bf16_t*)(WS(p) + OFF_A16)); }
.LBB0_853:
	s_cmp_lt_u32 s12, 21
	s_cselect_b64 s[10:11], -1, 0
	s_cmp_gt_u32 s12, 20
	s_mov_b64 s[0:1], -1
	v_readlane_b32 s20, v247, 46
	s_cbranch_scc0 .LBB0_881
	s_mov_b64 s[2:3], 0
	s_mov_b64 s[8:9], 0
	s_mov_b64 s[6:7], 0
	s_mov_b64 s[4:5], 0
	v_mov_b32_e32 v1, v147
	s_mov_b32 s0, s85
	v_ashrrev_i32_e32 v0, 5, v1
	v_and_b32_e32 v0, -2, v0
	v_lshl_add_u32 v0, s0, 4, v0
	s_mov_b32 s0, 0x8000
	v_cmp_gt_i32_e32 vcc, s0, v0
	s_and_saveexec_b64 s[0:1], vcc
	s_mov_b32 s14, 0x3a800000
	s_cbranch_execz .LBB0_857
	v_readlane_b32 s16, v248, 8
	v_readlane_b32 s18, v248, 10
	v_readlane_b32 s19, v248, 11
	s_add_u32 s8, s18, s8
	v_readlane_b32 s68, v248, 12
	s_addc_u32 s9, s19, s9
	s_lshl_b64 s[6:7], s[6:7], 2
	v_readlane_b32 s70, v248, 14
	v_readlane_b32 s71, v248, 15
	s_add_u32 s12, s70, s6
	s_addc_u32 s13, s71, s7
	v_readlane_b32 s6, v247, 49
	v_readlane_b32 s7, v247, 50
	s_ashr_i32 s7, s6, 31
	s_lshl_b64 s[6:7], s[6:7], 12
	s_add_u32 s6, s12, s6
	v_and_b32_e32 v1, 63, v1
	s_addc_u32 s7, s13, s7
	v_lshlrev_b32_e32 v2, 4, v1
	global_load_dwordx4 v[4:7], v2, s[6:7]
	global_load_dwordx4 v[8:11], v2, s[6:7] offset:1024
	global_load_dwordx4 v[12:15], v2, s[6:7] offset:2048
	global_load_dwordx4 v[16:19], v2, s[6:7] offset:3072
	s_add_u32 s4, s18, s4
	s_addc_u32 s5, s19, s5
	s_lshl_b64 s[2:3], s[2:3], 2
	v_readlane_b32 s17, v248, 9
	s_add_u32 s2, s16, s2
	s_addc_u32 s3, s17, s3
	v_lshl_add_u64 v[20:21], s[2:3], 0, v[2:3]
	v_lshlrev_b32_e32 v2, 2, v1
	v_xor_b32_e32 v32, 0x80, v2
	v_xor_b32_e32 v33, 64, v2
	v_xor_b32_e32 v34, 32, v2
	v_xor_b32_e32 v35, 16, v2
	v_xor_b32_e32 v36, 8, v2
	v_xor_b32_e32 v37, 4, v2
	v_lshlrev_b32_e32 v2, 3, v1
	v_lshl_add_u64 v[24:25], s[8:9], 0, v[2:3]
	s_mov_b64 s[2:3], 0xc000000
	v_lshl_add_u64 v[22:23], s[4:5], 0, v[2:3]
	v_lshl_add_u64 v[24:25], v[24:25], 0, s[2:3]
	s_mov_b64 s[2:3], 0
	v_readlane_b32 s69, v248, 13
	v_readlane_b32 s72, v248, 16
	v_readlane_b32 s73, v248, 17
	v_readlane_b32 s74, v248, 18
	v_readlane_b32 s75, v248, 19
	v_readlane_b32 s76, v248, 20
	v_readlane_b32 s77, v248, 21
	v_readlane_b32 s78, v248, 22
	v_readlane_b32 s79, v248, 23
	v_readlane_b32 s80, v248, 24
	v_readlane_b32 s81, v248, 25
	v_readlane_b32 s82, v248, 26
	v_readlane_b32 s83, v248, 27
	v_ashrrev_i32_e32 v209, 31, v0
	v_mov_b32_e32 v208, v0
	v_lshlrev_b64 v[210:211], 12, v[208:209]
	v_lshlrev_b64 v[208:209], 11, v[208:209]
	v_lshl_add_u64 v[208:209], v[24:25], 0, v[208:209]
	v_lshl_add_u64 v[210:211], v[20:21], 0, v[210:211]
	global_load_dwordx2 v[192:193], v[208:209], off
	global_load_dwordx2 v[194:195], v[208:209], off offset:512
	global_load_dwordx2 v[196:197], v[208:209], off offset:1024
	global_load_dwordx2 v[198:199], v[208:209], off offset:1536
	global_load_dwordx2 v[200:201], v[208:209], off offset:2048
	global_load_dwordx2 v[202:203], v[208:209], off offset:2560
	global_load_dwordx2 v[204:205], v[208:209], off offset:3072
	global_load_dwordx2 v[206:207], v[208:209], off offset:3584
	global_load_dwordx4 v[160:163], v[210:211], off nt
	global_load_dwordx4 v[164:167], v[210:211], off offset:1024 nt
	global_load_dwordx4 v[168:171], v[210:211], off offset:2048 nt
	global_load_dwordx4 v[172:175], v[210:211], off offset:3072 nt
	v_add_co_u32_e32 v210, vcc, 0x1000, v210
	s_nop 1
	v_addc_co_u32_e32 v211, vcc, 0, v211, vcc
	global_load_dwordx4 v[176:179], v[210:211], off nt
	global_load_dwordx4 v[180:183], v[210:211], off offset:1024 nt
	global_load_dwordx4 v[184:187], v[210:211], off offset:2048 nt
	global_load_dwordx4 v[188:191], v[210:211], off offset:3072 nt
	s_waitcnt vmcnt(0)
.LnB_loop:
	v_add_u32_e32 v216, s88, v0
	v_cmp_ge_i32_e32 vcc, s97, v216
	s_cbranch_vccz .LnB_nopf0
	v_ashrrev_i32_e32 v209, 31, v216
	v_mov_b32_e32 v208, v216
	v_lshlrev_b64 v[210:211], 12, v[208:209]
	v_lshlrev_b64 v[208:209], 11, v[208:209]
	v_lshl_add_u64 v[208:209], v[24:25], 0, v[208:209]
	v_lshl_add_u64 v[210:211], v[20:21], 0, v[210:211]
	global_load_dwordx2 v[96:97], v[208:209], off
	global_load_dwordx2 v[98:99], v[208:209], off offset:512
	global_load_dwordx2 v[100:101], v[208:209], off offset:1024
	global_load_dwordx2 v[102:103], v[208:209], off offset:1536
	global_load_dwordx2 v[104:105], v[208:209], off offset:2048
	global_load_dwordx2 v[106:107], v[208:209], off offset:2560
	global_load_dwordx2 v[108:109], v[208:209], off offset:3072
	global_load_dwordx2 v[110:111], v[208:209], off offset:3584
	global_load_dwordx4 v[64:67], v[210:211], off nt
	global_load_dwordx4 v[68:71], v[210:211], off offset:1024 nt
	global_load_dwordx4 v[72:75], v[210:211], off offset:2048 nt
	global_load_dwordx4 v[76:79], v[210:211], off offset:3072 nt
	v_add_co_u32_e32 v210, vcc, 0x1000, v210
	s_nop 1
	v_addc_co_u32_e32 v211, vcc, 0, v211, vcc
	global_load_dwordx4 v[80:83], v[210:211], off nt
	global_load_dwordx4 v[84:87], v[210:211], off offset:1024 nt
	global_load_dwordx4 v[88:91], v[210:211], off offset:2048 nt
	global_load_dwordx4 v[92:95], v[210:211], off offset:3072 nt
; __device__ __forceinline__ float lo_bf(unsigned u) { return __uint_as_float(u << 16); }
; __device__ __forceinline__ float hi_bf(unsigned u) { return __uint_as_float(u & 0xffff0000u); }
; __device__ __forceinline__ void rmsnorm_rows_bf16(int swave, const float* xsrc, const bf16_t* add, float* xdst, const float* g, bf16_t* out) {
;     ...
; #pragma unroll
;       for (int u = 0; u < 8; ++u) { v[u].x += lo_bf(av[u].x); v[u].y += hi_bf(av[u].x); v[u].z += lo_bf(av[u].y); v[u].w += hi_bf(av[u].y); }
;       float4* xw = (float4*)(xdst + (size_t)row * DM);
; #pragma unroll
;       for (int u = 0; u < 8; ++u) { const f32x4 t = {v[u].x, v[u].y, v[u].z, v[u].w}; __builtin_nontemporal_store(t, (f32x4*)xw + lane + 64 * u); }
;     }
; #pragma unroll
;     for (int u = 0; u < 4; ++u) {
;       s0 += v[u].x * v[u].x + v[u].y * v[u].y + v[u].z * v[u].z + v[u].w * v[u].w;
;       s1 += v[u + 4].x * v[u + 4].x + v[u + 4].y * v[u + 4].y + v[u + 4].z * v[u + 4].z + v[u + 4].w * v[u + 4].w;
;     }
; #pragma unroll
;     for (int o = 32; o > 0; o >>= 1) {
;       s0 += __int_as_float(__builtin_amdgcn_ds_bpermute((lane ^ o) << 2, __float_as_int(s0)));
;       s1 += __int_as_float(__builtin_amdgcn_ds_bpermute((lane ^ o) << 2, __float_as_int(s1)));
;     }
.LnB_nopf0:
	v_ashrrev_i32_e32 v1, 31, v0
	v_lshlrev_b64 v[212:213], 12, v[0:1]
	v_lshl_add_u64 v[212:213], v[20:21], 0, v[212:213]
	v_lshlrev_b64 v[214:215], 11, v[0:1]
	v_lshl_add_u64 v[214:215], v[22:23], 0, v[214:215]
	v_lshlrev_b32_e32 v112, 16, v192
	v_and_b32_e32 v113, 0xffff0000, v192
	v_lshlrev_b32_e32 v114, 16, v193
	v_and_b32_e32 v115, 0xffff0000, v193
	v_pk_add_f32 v[160:161], v[160:161], v[112:113]
	v_pk_add_f32 v[162:163], v[162:163], v[114:115]
	v_lshlrev_b32_e32 v116, 16, v194
	v_and_b32_e32 v117, 0xffff0000, v194
	v_lshlrev_b32_e32 v118, 16, v195
	v_and_b32_e32 v119, 0xffff0000, v195
	v_pk_add_f32 v[164:165], v[164:165], v[116:117]
	v_pk_add_f32 v[166:167], v[166:167], v[118:119]
	v_lshlrev_b32_e32 v120, 16, v196
	v_and_b32_e32 v121, 0xffff0000, v196
	v_lshlrev_b32_e32 v122, 16, v197
	v_and_b32_e32 v123, 0xffff0000, v197
	v_pk_add_f32 v[168:169], v[168:169], v[120:121]
	v_pk_add_f32 v[170:171], v[170:171], v[122:123]
	v_lshlrev_b32_e32 v124, 16, v198
	v_and_b32_e32 v125, 0xffff0000, v198
	v_lshlrev_b32_e32 v126, 16, v199
	v_and_b32_e32 v127, 0xffff0000, v199
	v_pk_add_f32 v[172:173], v[172:173], v[124:125]
	v_pk_add_f32 v[174:175], v[174:175], v[126:127]
	v_lshlrev_b32_e32 v112, 16, v200
	v_and_b32_e32 v113, 0xffff0000, v200
	v_lshlrev_b32_e32 v114, 16, v201
	v_and_b32_e32 v115, 0xffff0000, v201
	v_pk_add_f32 v[176:177], v[176:177], v[112:113]
	v_pk_add_f32 v[178:179], v[178:179], v[114:115]
	v_lshlrev_b32_e32 v116, 16, v202
	v_and_b32_e32 v117, 0xffff0000, v202
	v_lshlrev_b32_e32 v118, 16, v203
	v_and_b32_e32 v119, 0xffff0000, v203
	v_pk_add_f32 v[180:181], v[180:181], v[116:117]
	v_pk_add_f32 v[182:183], v[182:183], v[118:119]
	v_lshlrev_b32_e32 v120, 16, v204
	v_and_b32_e32 v121, 0xffff0000, v204
	v_lshlrev_b32_e32 v122, 16, v205
	v_and_b32_e32 v123, 0xffff0000, v205
	v_pk_add_f32 v[184:185], v[184:185], v[120:121]
	v_pk_add_f32 v[186:187], v[186:187], v[122:123]
	v_lshlrev_b32_e32 v124, 16, v206
	v_and_b32_e32 v125, 0xffff0000, v206
	v_lshlrev_b32_e32 v126, 16, v207
	v_and_b32_e32 v127, 0xffff0000, v207
	v_pk_add_f32 v[188:189], v[188:189], v[124:125]
	v_pk_add_f32 v[190:191], v[190:191], v[126:127]
	global_store_dwordx4 v[212:213], v[160:163], off nt
	global_store_dwordx4 v[212:213], v[164:167], off offset:1024 nt
	global_store_dwordx4 v[212:213], v[168:171], off offset:2048 nt
	global_store_dwordx4 v[212:213], v[172:175], off offset:3072 nt
	v_add_co_u32_e32 v212, vcc, 0x1000, v212
	s_nop 1
	v_addc_co_u32_e32 v213, vcc, 0, v213, vcc
	global_store_dwordx4 v[212:213], v[176:179], off nt
	global_store_dwordx4 v[212:213], v[180:183], off offset:1024 nt
	global_store_dwordx4 v[212:213], v[184:187], off offset:2048 nt
	global_store_dwordx4 v[212:213], v[188:191], off offset:3072 nt
	v_pk_mul_f32 v[128:129], v[160:161], v[160:161]
	v_pk_mul_f32 v[130:131], v[176:177], v[176:177]
	v_pk_fma_f32 v[128:129], v[162:163], v[162:163], v[128:129]
	v_pk_fma_f32 v[130:131], v[178:179], v[178:179], v[130:131]
	v_pk_fma_f32 v[128:129], v[164:165], v[164:165], v[128:129]
	v_pk_fma_f32 v[130:131], v[180:181], v[180:181], v[130:131]
	v_pk_fma_f32 v[128:129], v[166:167], v[166:167], v[128:129]
	v_pk_fma_f32 v[130:131], v[182:183], v[182:183], v[130:131]
	v_pk_fma_f32 v[128:129], v[168:169], v[168:169], v[128:129]
	v_pk_fma_f32 v[130:131], v[184:185], v[184:185], v[130:131]
	v_pk_fma_f32 v[128:129], v[170:171], v[170:171], v[128:129]
	v_pk_fma_f32 v[130:131], v[186:187], v[186:187], v[130:131]
	v_pk_fma_f32 v[128:129], v[172:173], v[172:173], v[128:129]
	v_pk_fma_f32 v[130:131], v[188:189], v[188:189], v[130:131]
	v_pk_fma_f32 v[128:129], v[174:175], v[174:175], v[128:129]
	v_pk_fma_f32 v[130:131], v[190:191], v[190:191], v[130:131]
	v_add_f32_e32 v218, v128, v129
	v_add_f32_e32 v219, v130, v131
	ds_bpermute_b32 v221, v32, v219
	ds_bpermute_b32 v220, v32, v218
	s_waitcnt lgkmcnt(0)
	v_pk_add_f32 v[218:219], v[218:219], v[220:221]
	ds_bpermute_b32 v221, v33, v219
	ds_bpermute_b32 v220, v33, v218
	s_waitcnt lgkmcnt(0)
	v_pk_add_f32 v[218:219], v[218:219], v[220:221]
	ds_bpermute_b32 v221, v34, v219
	ds_bpermute_b32 v220, v34, v218
	s_waitcnt lgkmcnt(0)
	v_pk_add_f32 v[218:219], v[218:219], v[220:221]
	ds_bpermute_b32 v221, v35, v219
	ds_bpermute_b32 v220, v35, v218
	s_waitcnt lgkmcnt(0)
	v_pk_add_f32 v[218:219], v[218:219], v[220:221]
	ds_bpermute_b32 v221, v36, v219
	ds_bpermute_b32 v220, v36, v218
	s_waitcnt lgkmcnt(0)
	v_pk_add_f32 v[218:219], v[218:219], v[220:221]
	ds_bpermute_b32 v221, v37, v219
	ds_bpermute_b32 v220, v37, v218
	s_waitcnt lgkmcnt(0)
; __device__ __forceinline__ unsigned pk2(float lo, float hi) { f32x2_t v = {lo, hi}; bf16x2_t b = __builtin_convertvector(v, bf16x2_t); return __builtin_bit_cast(unsigned, b); }
; __device__ __forceinline__ void rmsnorm_rows_bf16(int swave, const float* xsrc, const bf16_t* add, float* xdst, const float* g, bf16_t* out) {
;     ...
;     for (int o = 32; o > 0; o >>= 1) {
;       s0 += __int_as_float(__builtin_amdgcn_ds_bpermute((lane ^ o) << 2, __float_as_int(s0)));
;       s1 += __int_as_float(__builtin_amdgcn_ds_bpermute((lane ^ o) << 2, __float_as_int(s1)));
;     }
;     const float r0 = rsqrtf(s0 * (1.f / DM) + EPS), r1 = rsqrtf(s1 * (1.f / DM) + EPS);
; #pragma unroll
;     for (int u = 0; u < 8; ++u) {
;       const float r = u < 4 ? r0 : r1; const float4 g4 = gg[u & 3];
;       uint2 o; o.x = pk2(v[u].x * r * g4.x, v[u].y * r * g4.y); o.y = pk2(v[u].z * r * g4.z, v[u].w * r * g4.w);
;       *(uint2*)(out + (size_t)row * DM + (lane + 64 * u) * 4) = o;
;     }
	v_pk_add_f32 v[218:219], v[218:219], v[220:221]
	s_nop 0
	v_pk_fma_f32 v[218:219], v[218:219], s[14:15], v[132:133] op_sel_hi:[1,0,0]
	s_nop 0
	v_mul_f32_e32 v1, 0x4b800000, v218
	v_cmp_gt_f32_e32 vcc, s26, v218
	s_nop 1
	v_cndmask_b32_e32 v1, v218, v1, vcc
	v_rsq_f32_e32 v1, v1
	s_nop 0
	v_mul_f32_e32 v2, 0x45800000, v1
	v_cndmask_b32_e32 v222, v1, v2, vcc
	s_nop 0
	v_mul_f32_e32 v1, 0x4b800000, v219
	v_cmp_gt_f32_e32 vcc, s26, v219
	s_nop 1
	v_cndmask_b32_e32 v1, v219, v1, vcc
	v_rsq_f32_e32 v1, v1
	s_nop 0
	v_mul_f32_e32 v2, 0x45800000, v1
	v_cndmask_b32_e32 v224, v1, v2, vcc
	v_pk_mul_f32 v[112:113], v[160:161], v[222:223] op_sel_hi:[1,0]
	v_pk_mul_f32 v[114:115], v[162:163], v[222:223] op_sel_hi:[1,0]
	v_pk_mul_f32 v[112:113], v[4:5], v[112:113]
	v_pk_mul_f32 v[114:115], v[6:7], v[114:115]
	v_cvt_pk_bf16_f32 v226, v112, v113
	v_cvt_pk_bf16_f32 v227, v114, v115
	global_store_dwordx2 v[214:215], v[226:227], off
	v_pk_mul_f32 v[116:117], v[164:165], v[222:223] op_sel_hi:[1,0]
	v_pk_mul_f32 v[118:119], v[166:167], v[222:223] op_sel_hi:[1,0]
	v_pk_mul_f32 v[116:117], v[8:9], v[116:117]
	v_pk_mul_f32 v[118:119], v[10:11], v[118:119]
	v_cvt_pk_bf16_f32 v228, v116, v117
	v_cvt_pk_bf16_f32 v229, v118, v119
	global_store_dwordx2 v[214:215], v[228:229], off offset:512
	v_pk_mul_f32 v[120:121], v[168:169], v[222:223] op_sel_hi:[1,0]
	v_pk_mul_f32 v[122:123], v[170:171], v[222:223] op_sel_hi:[1,0]
	v_pk_mul_f32 v[120:121], v[12:13], v[120:121]
	v_pk_mul_f32 v[122:123], v[14:15], v[122:123]
	v_cvt_pk_bf16_f32 v230, v120, v121
	v_cvt_pk_bf16_f32 v231, v122, v123
	global_store_dwordx2 v[214:215], v[230:231], off offset:1024
	v_pk_mul_f32 v[124:125], v[172:173], v[222:223] op_sel_hi:[1,0]
	v_pk_mul_f32 v[126:127], v[174:175], v[222:223] op_sel_hi:[1,0]
	v_pk_mul_f32 v[124:125], v[16:17], v[124:125]
	v_pk_mul_f32 v[126:127], v[18:19], v[126:127]
	v_cvt_pk_bf16_f32 v232, v124, v125
	v_cvt_pk_bf16_f32 v233, v126, v127
	global_store_dwordx2 v[214:215], v[232:233], off offset:1536
	v_pk_mul_f32 v[112:113], v[176:177], v[224:225] op_sel_hi:[1,0]
	v_pk_mul_f32 v[114:115], v[178:179], v[224:225] op_sel_hi:[1,0]
	v_pk_mul_f32 v[112:113], v[4:5], v[112:113]
	v_pk_mul_f32 v[114:115], v[6:7], v[114:115]
	v_cvt_pk_bf16_f32 v226, v112, v113
	v_cvt_pk_bf16_f32 v227, v114, v115
	global_store_dwordx2 v[214:215], v[226:227], off offset:2048
	v_pk_mul_f32 v[116:117], v[180:181], v[224:225] op_sel_hi:[1,0]
	v_pk_mul_f32 v[118:119], v[182:183], v[224:225] op_sel_hi:[1,0]
	v_pk_mul_f32 v[116:117], v[8:9], v[116:117]
	v_pk_mul_f32 v[118:119], v[10:11], v[118:119]
	v_cvt_pk_bf16_f32 v228, v116, v117
	v_cvt_pk_bf16_f32 v229, v118, v119
	global_store_dwordx2 v[214:215], v[228:229], off offset:2560
	v_pk_mul_f32 v[120:121], v[184:185], v[224:225] op_sel_hi:[1,0]
	v_pk_mul_f32 v[122:123], v[186:187], v[224:225] op_sel_hi:[1,0]
	v_pk_mul_f32 v[120:121], v[12:13], v[120:121]
	v_pk_mul_f32 v[122:123], v[14:15], v[122:123]
	v_cvt_pk_bf16_f32 v230, v120, v121
	v_cvt_pk_bf16_f32 v231, v122, v123
	global_store_dwordx2 v[214:215], v[230:231], off offset:3072
	v_pk_mul_f32 v[124:125], v[188:189], v[224:225] op_sel_hi:[1,0]
	v_pk_mul_f32 v[126:127], v[190:191], v[224:225] op_sel_hi:[1,0]
	v_pk_mul_f32 v[124:125], v[16:17], v[124:125]
	v_pk_mul_f32 v[126:127], v[18:19], v[126:127]
	v_cvt_pk_bf16_f32 v232, v124, v125
	v_cvt_pk_bf16_f32 v233, v126, v127
	global_store_dwordx2 v[214:215], v[232:233], off offset:3584
	v_mov_b32_e32 v0, v216
	v_cmp_lt_i32_e32 vcc, s97, v0
	s_waitcnt vmcnt(16)
	s_or_b64 s[2:3], vcc, s[2:3]
	s_andn2_b64 exec, exec, s[2:3]
	s_cbranch_execz .LBB0_857
	v_add_u32_e32 v216, s88, v0
	v_cmp_ge_i32_e32 vcc, s97, v216
	s_cbranch_vccz .LnB_nopf1
	v_ashrrev_i32_e32 v209, 31, v216
	v_mov_b32_e32 v208, v216
	v_lshlrev_b64 v[210:211], 12, v[208:209]
	v_lshlrev_b64 v[208:209], 11, v[208:209]
	v_lshl_add_u64 v[208:209], v[24:25], 0, v[208:209]
	v_lshl_add_u64 v[210:211], v[20:21], 0, v[210:211]
	global_load_dwordx2 v[192:193], v[208:209], off
	global_load_dwordx2 v[194:195], v[208:209], off offset:512
	global_load_dwordx2 v[196:197], v[208:209], off offset:1024
	global_load_dwordx2 v[198:199], v[208:209], off offset:1536
	global_load_dwordx2 v[200:201], v[208:209], off offset:2048
	global_load_dwordx2 v[202:203], v[208:209], off offset:2560
	global_load_dwordx2 v[204:205], v[208:209], off offset:3072
	global_load_dwordx2 v[206:207], v[208:209], off offset:3584
	global_load_dwordx4 v[160:163], v[210:211], off nt
	global_load_dwordx4 v[164:167], v[210:211], off offset:1024 nt
	global_load_dwordx4 v[168:171], v[210:211], off offset:2048 nt
	global_load_dwordx4 v[172:175], v[210:211], off offset:3072 nt
	v_add_co_u32_e32 v210, vcc, 0x1000, v210
	s_nop 1
	v_addc_co_u32_e32 v211, vcc, 0, v211, vcc
	global_load_dwordx4 v[176:179], v[210:211], off nt
	global_load_dwordx4 v[180:183], v[210:211], off offset:1024 nt
	global_load_dwordx4 v[184:187], v[210:211], off offset:2048 nt
	global_load_dwordx4 v[188:191], v[210:211], off offset:3072 nt
; __device__ __forceinline__ float lo_bf(unsigned u) { return __uint_as_float(u << 16); }
; __device__ __forceinline__ float hi_bf(unsigned u) { return __uint_as_float(u & 0xffff0000u); }
; __device__ __forceinline__ void rmsnorm_rows_bf16(int swave, const float* xsrc, const bf16_t* add, float* xdst, const float* g, bf16_t* out) {
;     ...
;     const float4* xr = (const float4*)(xsrc + (size_t)row * DM);
;     float4 v[8]; float s0 = 0.f, s1 = 0.f;
; #pragma unroll
;     for (int u = 0; u < 8; ++u) { const f32x4 t = __builtin_nontemporal_load((const f32x4*)xr + lane + 64 * u); v[u] = make_float4(t[0], t[1], t[2], t[3]); }
;     if (add) {
;       const uint2* ar = (const uint2*)(add + (size_t)row * DM);
;       uint2 av[8];
; #pragma unroll
;       for (int u = 0; u < 8; ++u) av[u] = ar[lane + 64 * u];
; #pragma unroll
;       for (int u = 0; u < 8; ++u) { v[u].x += lo_bf(av[u].x); v[u].y += hi_bf(av[u].x); v[u].z += lo_bf(av[u].y); v[u].w += hi_bf(av[u].y); }
;       float4* xw = (float4*)(xdst + (size_t)row * DM);
; #pragma unroll
;       for (int u = 0; u < 8; ++u) { const f32x4 t = {v[u].x, v[u].y, v[u].z, v[u].w}; __builtin_nontemporal_store(t, (f32x4*)xw + lane + 64 * u); }
;     }
; #pragma unroll
;     for (int u = 0; u < 4; ++u) {
;       s0 += v[u].x * v[u].x + v[u].y * v[u].y + v[u].z * v[u].z + v[u].w * v[u].w;
;       s1 += v[u + 4].x * v[u + 4].x + v[u + 4].y * v[u + 4].y + v[u + 4].z * v[u + 4].z + v[u + 4].w * v[u + 4].w;
;     }
; #pragma unroll
;     for (int o = 32; o > 0; o >>= 1) {
;       s0 += __int_as_float(__builtin_amdgcn_ds_bpermute((lane ^ o) << 2, __float_as_int(s0)));
;       s1 += __int_as_float(__builtin_amdgcn_ds_bpermute((lane ^ o) << 2, __float_as_int(s1)));
;     }
.LnB_nopf1:
	v_ashrrev_i32_e32 v1, 31, v0
	v_lshlrev_b64 v[212:213], 12, v[0:1]
	v_lshl_add_u64 v[212:213], v[20:21], 0, v[212:213]
	v_lshlrev_b64 v[214:215], 11, v[0:1]
	v_lshl_add_u64 v[214:215], v[22:23], 0, v[214:215]
	v_lshlrev_b32_e32 v112, 16, v96
	v_and_b32_e32 v113, 0xffff0000, v96
	v_lshlrev_b32_e32 v114, 16, v97
	v_and_b32_e32 v115, 0xffff0000, v97
	v_pk_add_f32 v[64:65], v[64:65], v[112:113]
	v_pk_add_f32 v[66:67], v[66:67], v[114:115]
	v_lshlrev_b32_e32 v116, 16, v98
	v_and_b32_e32 v117, 0xffff0000, v98
	v_lshlrev_b32_e32 v118, 16, v99
	v_and_b32_e32 v119, 0xffff0000, v99
	v_pk_add_f32 v[68:69], v[68:69], v[116:117]
	v_pk_add_f32 v[70:71], v[70:71], v[118:119]
	v_lshlrev_b32_e32 v120, 16, v100
	v_and_b32_e32 v121, 0xffff0000, v100
	v_lshlrev_b32_e32 v122, 16, v101
	v_and_b32_e32 v123, 0xffff0000, v101
	v_pk_add_f32 v[72:73], v[72:73], v[120:121]
	v_pk_add_f32 v[74:75], v[74:75], v[122:123]
	v_lshlrev_b32_e32 v124, 16, v102
	v_and_b32_e32 v125, 0xffff0000, v102
	v_lshlrev_b32_e32 v126, 16, v103
	v_and_b32_e32 v127, 0xffff0000, v103
	v_pk_add_f32 v[76:77], v[76:77], v[124:125]
	v_pk_add_f32 v[78:79], v[78:79], v[126:127]
	v_lshlrev_b32_e32 v112, 16, v104
	v_and_b32_e32 v113, 0xffff0000, v104
	v_lshlrev_b32_e32 v114, 16, v105
	v_and_b32_e32 v115, 0xffff0000, v105
	v_pk_add_f32 v[80:81], v[80:81], v[112:113]
	v_pk_add_f32 v[82:83], v[82:83], v[114:115]
	v_lshlrev_b32_e32 v116, 16, v106
	v_and_b32_e32 v117, 0xffff0000, v106
	v_lshlrev_b32_e32 v118, 16, v107
	v_and_b32_e32 v119, 0xffff0000, v107
	v_pk_add_f32 v[84:85], v[84:85], v[116:117]
	v_pk_add_f32 v[86:87], v[86:87], v[118:119]
	v_lshlrev_b32_e32 v120, 16, v108
	v_and_b32_e32 v121, 0xffff0000, v108
	v_lshlrev_b32_e32 v122, 16, v109
	v_and_b32_e32 v123, 0xffff0000, v109
	v_pk_add_f32 v[88:89], v[88:89], v[120:121]
	v_pk_add_f32 v[90:91], v[90:91], v[122:123]
	v_lshlrev_b32_e32 v124, 16, v110
	v_and_b32_e32 v125, 0xffff0000, v110
	v_lshlrev_b32_e32 v126, 16, v111
	v_and_b32_e32 v127, 0xffff0000, v111
	v_pk_add_f32 v[92:93], v[92:93], v[124:125]
	v_pk_add_f32 v[94:95], v[94:95], v[126:127]
	global_store_dwordx4 v[212:213], v[64:67], off nt
	global_store_dwordx4 v[212:213], v[68:71], off offset:1024 nt
	global_store_dwordx4 v[212:213], v[72:75], off offset:2048 nt
	global_store_dwordx4 v[212:213], v[76:79], off offset:3072 nt
	v_add_co_u32_e32 v212, vcc, 0x1000, v212
	s_nop 1
	v_addc_co_u32_e32 v213, vcc, 0, v213, vcc
	global_store_dwordx4 v[212:213], v[80:83], off nt
	global_store_dwordx4 v[212:213], v[84:87], off offset:1024 nt
	global_store_dwordx4 v[212:213], v[88:91], off offset:2048 nt
	global_store_dwordx4 v[212:213], v[92:95], off offset:3072 nt
	v_pk_mul_f32 v[128:129], v[64:65], v[64:65]
	v_pk_mul_f32 v[130:131], v[80:81], v[80:81]
	v_pk_fma_f32 v[128:129], v[66:67], v[66:67], v[128:129]
	v_pk_fma_f32 v[130:131], v[82:83], v[82:83], v[130:131]
	v_pk_fma_f32 v[128:129], v[68:69], v[68:69], v[128:129]
	v_pk_fma_f32 v[130:131], v[84:85], v[84:85], v[130:131]
	v_pk_fma_f32 v[128:129], v[70:71], v[70:71], v[128:129]
	v_pk_fma_f32 v[130:131], v[86:87], v[86:87], v[130:131]
	v_pk_fma_f32 v[128:129], v[72:73], v[72:73], v[128:129]
	v_pk_fma_f32 v[130:131], v[88:89], v[88:89], v[130:131]
	v_pk_fma_f32 v[128:129], v[74:75], v[74:75], v[128:129]
	v_pk_fma_f32 v[130:131], v[90:91], v[90:91], v[130:131]
	v_pk_fma_f32 v[128:129], v[76:77], v[76:77], v[128:129]
	v_pk_fma_f32 v[130:131], v[92:93], v[92:93], v[130:131]
	v_pk_fma_f32 v[128:129], v[78:79], v[78:79], v[128:129]
	v_pk_fma_f32 v[130:131], v[94:95], v[94:95], v[130:131]
	v_add_f32_e32 v218, v128, v129
	v_add_f32_e32 v219, v130, v131
	ds_bpermute_b32 v221, v32, v219
	ds_bpermute_b32 v220, v32, v218
	s_waitcnt lgkmcnt(0)
	v_pk_add_f32 v[218:219], v[218:219], v[220:221]
	ds_bpermute_b32 v221, v33, v219
	ds_bpermute_b32 v220, v33, v218
	s_waitcnt lgkmcnt(0)
	v_pk_add_f32 v[218:219], v[218:219], v[220:221]
	ds_bpermute_b32 v221, v34, v219
	ds_bpermute_b32 v220, v34, v218
	s_waitcnt lgkmcnt(0)
; __device__ __forceinline__ unsigned pk2(float lo, float hi) { f32x2_t v = {lo, hi}; bf16x2_t b = __builtin_convertvector(v, bf16x2_t); return __builtin_bit_cast(unsigned, b); }
; __device__ __forceinline__ void rmsnorm_rows_bf16(int swave, const float* xsrc, const bf16_t* add, float* xdst, const float* g, bf16_t* out) {
;     ...
;     for (int o = 32; o > 0; o >>= 1) {
;       s0 += __int_as_float(__builtin_amdgcn_ds_bpermute((lane ^ o) << 2, __float_as_int(s0)));
;       s1 += __int_as_float(__builtin_amdgcn_ds_bpermute((lane ^ o) << 2, __float_as_int(s1)));
;     }
;     const float r0 = rsqrtf(s0 * (1.f / DM) + EPS), r1 = rsqrtf(s1 * (1.f / DM) + EPS);
; #pragma unroll
;     for (int u = 0; u < 8; ++u) {
;       const float r = u < 4 ? r0 : r1; const float4 g4 = gg[u & 3];
;       uint2 o; o.x = pk2(v[u].x * r * g4.x, v[u].y * r * g4.y); o.y = pk2(v[u].z * r * g4.z, v[u].w * r * g4.w);
;       *(uint2*)(out + (size_t)row * DM + (lane + 64 * u) * 4) = o;
;     }
	v_pk_add_f32 v[218:219], v[218:219], v[220:221]
	ds_bpermute_b32 v221, v35, v219
	ds_bpermute_b32 v220, v35, v218
	s_waitcnt lgkmcnt(0)
	v_pk_add_f32 v[218:219], v[218:219], v[220:221]
	ds_bpermute_b32 v221, v36, v219
	ds_bpermute_b32 v220, v36, v218
	s_waitcnt lgkmcnt(0)
	v_pk_add_f32 v[218:219], v[218:219], v[220:221]
	ds_bpermute_b32 v221, v37, v219
	ds_bpermute_b32 v220, v37, v218
	s_waitcnt lgkmcnt(0)
	v_pk_add_f32 v[218:219], v[218:219], v[220:221]
	s_nop 0
	v_pk_fma_f32 v[218:219], v[218:219], s[14:15], v[132:133] op_sel_hi:[1,0,0]
	s_nop 0
	v_mul_f32_e32 v1, 0x4b800000, v218
	v_cmp_gt_f32_e32 vcc, s26, v218
	s_nop 1
	v_cndmask_b32_e32 v1, v218, v1, vcc
	v_rsq_f32_e32 v1, v1
	s_nop 0
	v_mul_f32_e32 v2, 0x45800000, v1
	v_cndmask_b32_e32 v222, v1, v2, vcc
	s_nop 0
	v_mul_f32_e32 v1, 0x4b800000, v219
	v_cmp_gt_f32_e32 vcc, s26, v219
	s_nop 1
	v_cndmask_b32_e32 v1, v219, v1, vcc
	v_rsq_f32_e32 v1, v1
	s_nop 0
	v_mul_f32_e32 v2, 0x45800000, v1
	v_cndmask_b32_e32 v224, v1, v2, vcc
	v_pk_mul_f32 v[112:113], v[64:65], v[222:223] op_sel_hi:[1,0]
	v_pk_mul_f32 v[114:115], v[66:67], v[222:223] op_sel_hi:[1,0]
	v_pk_mul_f32 v[112:113], v[4:5], v[112:113]
	v_pk_mul_f32 v[114:115], v[6:7], v[114:115]
	v_cvt_pk_bf16_f32 v226, v112, v113
	v_cvt_pk_bf16_f32 v227, v114, v115
	global_store_dwordx2 v[214:215], v[226:227], off
	v_pk_mul_f32 v[116:117], v[68:69], v[222:223] op_sel_hi:[1,0]
	v_pk_mul_f32 v[118:119], v[70:71], v[222:223] op_sel_hi:[1,0]
	v_pk_mul_f32 v[116:117], v[8:9], v[116:117]
	v_pk_mul_f32 v[118:119], v[10:11], v[118:119]
	v_cvt_pk_bf16_f32 v228, v116, v117
	v_cvt_pk_bf16_f32 v229, v118, v119
	global_store_dwordx2 v[214:215], v[228:229], off offset:512
	v_pk_mul_f32 v[120:121], v[72:73], v[222:223] op_sel_hi:[1,0]
	v_pk_mul_f32 v[122:123], v[74:75], v[222:223] op_sel_hi:[1,0]
	v_pk_mul_f32 v[120:121], v[12:13], v[120:121]
	v_pk_mul_f32 v[122:123], v[14:15], v[122:123]
	v_cvt_pk_bf16_f32 v230, v120, v121
	v_cvt_pk_bf16_f32 v231, v122, v123
	global_store_dwordx2 v[214:215], v[230:231], off offset:1024
	v_pk_mul_f32 v[124:125], v[76:77], v[222:223] op_sel_hi:[1,0]
	v_pk_mul_f32 v[126:127], v[78:79], v[222:223] op_sel_hi:[1,0]
	v_pk_mul_f32 v[124:125], v[16:17], v[124:125]
	v_pk_mul_f32 v[126:127], v[18:19], v[126:127]
	v_cvt_pk_bf16_f32 v232, v124, v125
	v_cvt_pk_bf16_f32 v233, v126, v127
	global_store_dwordx2 v[214:215], v[232:233], off offset:1536
	v_pk_mul_f32 v[112:113], v[80:81], v[224:225] op_sel_hi:[1,0]
	v_pk_mul_f32 v[114:115], v[82:83], v[224:225] op_sel_hi:[1,0]
	v_pk_mul_f32 v[112:113], v[4:5], v[112:113]
	v_pk_mul_f32 v[114:115], v[6:7], v[114:115]
	v_cvt_pk_bf16_f32 v226, v112, v113
	v_cvt_pk_bf16_f32 v227, v114, v115
	global_store_dwordx2 v[214:215], v[226:227], off offset:2048
	v_pk_mul_f32 v[116:117], v[84:85], v[224:225] op_sel_hi:[1,0]
	v_pk_mul_f32 v[118:119], v[86:87], v[224:225] op_sel_hi:[1,0]
	v_pk_mul_f32 v[116:117], v[8:9], v[116:117]
	v_pk_mul_f32 v[118:119], v[10:11], v[118:119]
	v_cvt_pk_bf16_f32 v228, v116, v117
	v_cvt_pk_bf16_f32 v229, v118, v119
	global_store_dwordx2 v[214:215], v[228:229], off offset:2560
	v_pk_mul_f32 v[120:121], v[88:89], v[224:225] op_sel_hi:[1,0]
	v_pk_mul_f32 v[122:123], v[90:91], v[224:225] op_sel_hi:[1,0]
	v_pk_mul_f32 v[120:121], v[12:13], v[120:121]
	v_pk_mul_f32 v[122:123], v[14:15], v[122:123]
	v_cvt_pk_bf16_f32 v230, v120, v121
	v_cvt_pk_bf16_f32 v231, v122, v123
	global_store_dwordx2 v[214:215], v[230:231], off offset:3072
	v_pk_mul_f32 v[124:125], v[92:93], v[224:225] op_sel_hi:[1,0]
	v_pk_mul_f32 v[126:127], v[94:95], v[224:225] op_sel_hi:[1,0]
	v_pk_mul_f32 v[124:125], v[16:17], v[124:125]
	v_pk_mul_f32 v[126:127], v[18:19], v[126:127]
	v_cvt_pk_bf16_f32 v232, v124, v125
	v_cvt_pk_bf16_f32 v233, v126, v127
	global_store_dwordx2 v[214:215], v[232:233], off offset:3584
	v_mov_b32_e32 v0, v216
	v_cmp_lt_i32_e32 vcc, s97, v0
	s_waitcnt vmcnt(16)
	s_or_b64 s[2:3], vcc, s[2:3]
	s_andn2_b64 exec, exec, s[2:3]
	s_cbranch_execnz .LnB_loop

; __device__ __forceinline__ int BIDX() { int t = blockIdx.x; asm volatile("" : "+s"(t)); return t; }
; __device__ __forceinline__ float lo_bf(unsigned u) { return __uint_as_float(u << 16); }
; __device__ __forceinline__ float hi_bf(unsigned u) { return __uint_as_float(u & 0xffff0000u); }
; __device__ __forceinline__ void rmsnorm_rows_bf16(int swave, const float* xsrc, const bf16_t* add, float* xdst, const float* g, bf16_t* out) {
;   const int tidx = TIDX(swave);
;   const int bidx = BIDX();
;   const int wave = tidx >> 6, lane = tidx & 63;
;   float4 gg[4];
; #pragma unroll
;   for (int u = 0; u < 4; ++u) gg[u] = ((const float4*)g)[lane + 64 * u];
;   for (int row = (bidx * 8 + wave) * 2; row < TOK; row += gridDim.x * 16) {
;     const float4* xr = (const float4*)(xsrc + (size_t)row * DM);
;     float4 v[8]; float s0 = 0.f, s1 = 0.f;
; #pragma unroll
;     for (int u = 0; u < 8; ++u) { const f32x4 t = __builtin_nontemporal_load((const f32x4*)xr + lane + 64 * u); v[u] = make_float4(t[0], t[1], t[2], t[3]); }
;     if (add) {
;       const uint2* ar = (const uint2*)(add + (size_t)row * DM);
;       uint2 av[8];
; #pragma unroll
;       for (int u = 0; u < 8; ++u) av[u] = ar[lane + 64 * u];
; #pragma unroll
;       for (int u = 0; u < 8; ++u) { v[u].x += lo_bf(av[u].x); v[u].y += hi_bf(av[u].x); v[u].z += lo_bf(av[u].y); v[u].w += hi_bf(av[u].y); }
;       float4* xw = (float4*)(xdst + (size_t)row * DM);
; #pragma unroll
;       for (int u = 0; u < 8; ++u) { const f32x4 t = {v[u].x, v[u].y, v[u].z, v[u].w}; __builtin_nontemporal_store(t, (f32x4*)xw + lane + 64 * u); }
;     }
; #pragma unroll
;     for (int u = 0; u < 4; ++u) {
;       s0 += v[u].x * v[u].x + v[u].y * v[u].y + v[u].z * v[u].z + v[u].w * v[u].w;
;       s1 += v[u + 4].x * v[u + 4].x + v[u + 4].y * v[u + 4].y + v[u + 4].z * v[u + 4].z + v[u + 4].w * v[u + 4].w;
;     }
; #pragma unroll
;     for (int o = 32; o > 0; o >>= 1) {
;       s0 += __int_as_float(__builtin_amdgcn_ds_bpermute((lane ^ o) << 2, __float_as_int(s0)));
;       s1 += __int_as_float(__builtin_amdgcn_ds_bpermute((lane ^ o) << 2, __float_as_int(s1)));
;     }
.LBB0_882:
	s_mov_b64 s[0:1], 0
	s_mov_b64 s[6:7], 0
	s_mov_b64 s[4:5], 0
	v_mov_b32_e32 v1, v147
	s_mov_b32 s2, s85
	v_ashrrev_i32_e32 v0, 5, v1
	v_and_b32_e32 v0, -2, v0
	v_lshl_add_u32 v0, s2, 4, v0
	s_mov_b32 s2, 0x8000
	v_cmp_gt_i32_e32 vcc, s2, v0
	s_and_saveexec_b64 s[2:3], vcc
	s_mov_b32 s16, 0x3a800000
	s_cbranch_execz .LBB0_885
	v_readlane_b32 s68, v248, 12
	s_lshl_b64 s[6:7], s[6:7], 2
	v_readlane_b32 s70, v248, 14
	v_readlane_b32 s71, v248, 15
	s_add_u32 s6, s70, s6
	v_and_b32_e32 v1, 63, v1
	s_addc_u32 s7, s71, s7
	v_lshlrev_b32_e32 v2, 4, v1
	global_load_dwordx4 v[4:7], v2, s[6:7]
	global_load_dwordx4 v[8:11], v2, s[6:7] offset:1024
	global_load_dwordx4 v[12:15], v2, s[6:7] offset:2048
	global_load_dwordx4 v[16:19], v2, s[6:7] offset:3072
	v_readlane_b32 s12, v248, 8
	v_readlane_b32 s14, v248, 10
	v_readlane_b32 s15, v248, 11
	s_add_u32 s4, s14, s4
	s_addc_u32 s5, s15, s5
	s_lshl_b64 s[0:1], s[0:1], 2
	v_readlane_b32 s69, v248, 13
	s_add_u32 s0, s68, s0
	s_addc_u32 s1, s69, s1
	v_lshl_add_u64 v[52:53], s[0:1], 0, v[2:3]
	v_lshlrev_b32_e32 v2, 2, v1
	s_waitcnt vmcnt(0)
	v_xor_b32_e32 v57, 0x80, v2
	v_xor_b32_e32 v58, 64, v2
	v_xor_b32_e32 v59, 32, v2
	v_xor_b32_e32 v60, 16, v2
	v_xor_b32_e32 v61, 8, v2
	v_xor_b32_e32 v62, 4, v2
	v_lshlrev_b32_e32 v2, 3, v1
	v_lshl_add_u64 v[54:55], s[4:5], 0, v[2:3]
	s_mov_b64 s[4:5], 0
	v_readlane_b32 s72, v248, 16
	v_readlane_b32 s73, v248, 17
	v_readlane_b32 s74, v248, 18
	v_readlane_b32 s75, v248, 19
	v_readlane_b32 s76, v248, 20
	v_readlane_b32 s77, v248, 21
	v_readlane_b32 s78, v248, 22
	v_readlane_b32 s79, v248, 23
	v_readlane_b32 s80, v248, 24
	v_readlane_b32 s81, v248, 25
	v_readlane_b32 s82, v248, 26
	v_readlane_b32 s83, v248, 27
	v_readlane_b32 s13, v248, 9
	v_ashrrev_i32_e32 v209, 31, v0
	v_mov_b32_e32 v208, v0
	v_lshlrev_b64 v[210:211], 12, v[208:209]
	v_lshl_add_u64 v[210:211], v[52:53], 0, v[210:211]
	global_load_dwordx4 v[160:163], v[210:211], off nt
	global_load_dwordx4 v[164:167], v[210:211], off offset:1024 nt
	global_load_dwordx4 v[168:171], v[210:211], off offset:2048 nt
	global_load_dwordx4 v[172:175], v[210:211], off offset:3072 nt
	v_add_co_u32_e32 v210, vcc, 0x1000, v210
	s_nop 1
	v_addc_co_u32_e32 v211, vcc, 0, v211, vcc
	global_load_dwordx4 v[176:179], v[210:211], off nt
	global_load_dwordx4 v[180:183], v[210:211], off offset:1024 nt
	global_load_dwordx4 v[184:187], v[210:211], off offset:2048 nt
	global_load_dwordx4 v[188:191], v[210:211], off offset:3072 nt
	s_waitcnt vmcnt(0)
.LnC_loop:
	v_add_u32_e32 v216, s88, v0
	v_cmp_ge_i32_e32 vcc, s97, v216
	s_cbranch_vccz .LnC_nopf0
	v_ashrrev_i32_e32 v209, 31, v216
	v_mov_b32_e32 v208, v216
	v_lshlrev_b64 v[210:211], 12, v[208:209]
	v_lshl_add_u64 v[210:211], v[52:53], 0, v[210:211]
	global_load_dwordx4 v[64:67], v[210:211], off nt
	global_load_dwordx4 v[68:71], v[210:211], off offset:1024 nt
	global_load_dwordx4 v[72:75], v[210:211], off offset:2048 nt
	global_load_dwordx4 v[76:79], v[210:211], off offset:3072 nt
	v_add_co_u32_e32 v210, vcc, 0x1000, v210
	s_nop 1
	v_addc_co_u32_e32 v211, vcc, 0, v211, vcc
	global_load_dwordx4 v[80:83], v[210:211], off nt
	global_load_dwordx4 v[84:87], v[210:211], off offset:1024 nt
	global_load_dwordx4 v[88:91], v[210:211], off offset:2048 nt
	global_load_dwordx4 v[92:95], v[210:211], off offset:3072 nt
.LnC_nopf0:
	v_ashrrev_i32_e32 v1, 31, v0
	v_lshlrev_b64 v[214:215], 11, v[0:1]
	v_lshl_add_u64 v[214:215], v[54:55], 0, v[214:215]
	v_pk_mul_f32 v[128:129], v[160:161], v[160:161]
	v_pk_mul_f32 v[130:131], v[176:177], v[176:177]
	v_pk_fma_f32 v[128:129], v[162:163], v[162:163], v[128:129]
	v_pk_fma_f32 v[130:131], v[178:179], v[178:179], v[130:131]
	v_pk_fma_f32 v[128:129], v[164:165], v[164:165], v[128:129]
	v_pk_fma_f32 v[130:131], v[180:181], v[180:181], v[130:131]
	v_pk_fma_f32 v[128:129], v[166:167], v[166:167], v[128:129]
	v_pk_fma_f32 v[130:131], v[182:183], v[182:183], v[130:131]
	v_pk_fma_f32 v[128:129], v[168:169], v[168:169], v[128:129]
	v_pk_fma_f32 v[130:131], v[184:185], v[184:185], v[130:131]
	v_pk_fma_f32 v[128:129], v[170:171], v[170:171], v[128:129]
	v_pk_fma_f32 v[130:131], v[186:187], v[186:187], v[130:131]
	v_pk_fma_f32 v[128:129], v[172:173], v[172:173], v[128:129]
	v_pk_fma_f32 v[130:131], v[188:189], v[188:189], v[130:131]
	v_pk_fma_f32 v[128:129], v[174:175], v[174:175], v[128:129]
	v_pk_fma_f32 v[130:131], v[190:191], v[190:191], v[130:131]
	v_add_f32_e32 v218, v128, v129
	v_add_f32_e32 v219, v130, v131
	ds_bpermute_b32 v221, v57, v219
	ds_bpermute_b32 v220, v57, v218
	s_waitcnt lgkmcnt(0)
	v_pk_add_f32 v[218:219], v[218:219], v[220:221]
	ds_bpermute_b32 v221, v58, v219
	ds_bpermute_b32 v220, v58, v218
	s_waitcnt lgkmcnt(0)
	v_pk_add_f32 v[218:219], v[218:219], v[220:221]
	ds_bpermute_b32 v221, v59, v219
	ds_bpermute_b32 v220, v59, v218
	s_waitcnt lgkmcnt(0)
	v_pk_add_f32 v[218:219], v[218:219], v[220:221]
	ds_bpermute_b32 v221, v60, v219
	ds_bpermute_b32 v220, v60, v218
	s_waitcnt lgkmcnt(0)
	v_pk_add_f32 v[218:219], v[218:219], v[220:221]
	ds_bpermute_b32 v221, v61, v219
	ds_bpermute_b32 v220, v61, v218
	s_waitcnt lgkmcnt(0)
	v_pk_add_f32 v[218:219], v[218:219], v[220:221]
	ds_bpermute_b32 v221, v62, v219
	ds_bpermute_b32 v220, v62, v218
	s_waitcnt lgkmcnt(0)
; __device__ __forceinline__ unsigned pk2(float lo, float hi) { f32x2_t v = {lo, hi}; bf16x2_t b = __builtin_convertvector(v, bf16x2_t); return __builtin_bit_cast(unsigned, b); }
; __device__ __forceinline__ void rmsnorm_rows_bf16(int swave, const float* xsrc, const bf16_t* add, float* xdst, const float* g, bf16_t* out) {
;     ...
;     for (int o = 32; o > 0; o >>= 1) {
;       s0 += __int_as_float(__builtin_amdgcn_ds_bpermute((lane ^ o) << 2, __float_as_int(s0)));
;       s1 += __int_as_float(__builtin_amdgcn_ds_bpermute((lane ^ o) << 2, __float_as_int(s1)));
;     }
;     const float r0 = rsqrtf(s0 * (1.f / DM) + EPS), r1 = rsqrtf(s1 * (1.f / DM) + EPS);
; #pragma unroll
;     for (int u = 0; u < 8; ++u) {
;       const float r = u < 4 ? r0 : r1; const float4 g4 = gg[u & 3];
;       uint2 o; o.x = pk2(v[u].x * r * g4.x, v[u].y * r * g4.y); o.y = pk2(v[u].z * r * g4.z, v[u].w * r * g4.w);
;       *(uint2*)(out + (size_t)row * DM + (lane + 64 * u) * 4) = o;
;     }
	v_pk_add_f32 v[218:219], v[218:219], v[220:221]
	s_nop 0
	v_pk_fma_f32 v[218:219], v[218:219], s[16:17], v[132:133] op_sel_hi:[1,0,0]
	s_nop 0
	v_mul_f32_e32 v1, 0x4b800000, v218
	v_cmp_gt_f32_e32 vcc, s26, v218
	s_nop 1
	v_cndmask_b32_e32 v1, v218, v1, vcc
	v_rsq_f32_e32 v1, v1
	s_nop 0
	v_mul_f32_e32 v2, 0x45800000, v1
	v_cndmask_b32_e32 v222, v1, v2, vcc
	s_nop 0
	v_mul_f32_e32 v1, 0x4b800000, v219
	v_cmp_gt_f32_e32 vcc, s26, v219
	s_nop 1
	v_cndmask_b32_e32 v1, v219, v1, vcc
	v_rsq_f32_e32 v1, v1
	s_nop 0
	v_mul_f32_e32 v2, 0x45800000, v1
	v_cndmask_b32_e32 v224, v1, v2, vcc
	v_pk_mul_f32 v[112:113], v[160:161], v[222:223] op_sel_hi:[1,0]
	v_pk_mul_f32 v[114:115], v[162:163], v[222:223] op_sel_hi:[1,0]
	v_pk_mul_f32 v[112:113], v[4:5], v[112:113]
	v_pk_mul_f32 v[114:115], v[6:7], v[114:115]
	v_cvt_pk_bf16_f32 v226, v112, v113
	v_cvt_pk_bf16_f32 v227, v114, v115
	global_store_dwordx2 v[214:215], v[226:227], off
	v_pk_mul_f32 v[116:117], v[164:165], v[222:223] op_sel_hi:[1,0]
	v_pk_mul_f32 v[118:119], v[166:167], v[222:223] op_sel_hi:[1,0]
	v_pk_mul_f32 v[116:117], v[8:9], v[116:117]
	v_pk_mul_f32 v[118:119], v[10:11], v[118:119]
	v_cvt_pk_bf16_f32 v228, v116, v117
	v_cvt_pk_bf16_f32 v229, v118, v119
	global_store_dwordx2 v[214:215], v[228:229], off offset:512
	v_pk_mul_f32 v[120:121], v[168:169], v[222:223] op_sel_hi:[1,0]
	v_pk_mul_f32 v[122:123], v[170:171], v[222:223] op_sel_hi:[1,0]
	v_pk_mul_f32 v[120:121], v[12:13], v[120:121]
	v_pk_mul_f32 v[122:123], v[14:15], v[122:123]
	v_cvt_pk_bf16_f32 v230, v120, v121
	v_cvt_pk_bf16_f32 v231, v122, v123
	global_store_dwordx2 v[214:215], v[230:231], off offset:1024
	v_pk_mul_f32 v[124:125], v[172:173], v[222:223] op_sel_hi:[1,0]
	v_pk_mul_f32 v[126:127], v[174:175], v[222:223] op_sel_hi:[1,0]
	v_pk_mul_f32 v[124:125], v[16:17], v[124:125]
	v_pk_mul_f32 v[126:127], v[18:19], v[126:127]
	v_cvt_pk_bf16_f32 v232, v124, v125
	v_cvt_pk_bf16_f32 v233, v126, v127
	global_store_dwordx2 v[214:215], v[232:233], off offset:1536
	v_pk_mul_f32 v[112:113], v[176:177], v[224:225] op_sel_hi:[1,0]
	v_pk_mul_f32 v[114:115], v[178:179], v[224:225] op_sel_hi:[1,0]
	v_pk_mul_f32 v[112:113], v[4:5], v[112:113]
	v_pk_mul_f32 v[114:115], v[6:7], v[114:115]
	v_cvt_pk_bf16_f32 v226, v112, v113
	v_cvt_pk_bf16_f32 v227, v114, v115
	global_store_dwordx2 v[214:215], v[226:227], off offset:2048
	v_pk_mul_f32 v[116:117], v[180:181], v[224:225] op_sel_hi:[1,0]
	v_pk_mul_f32 v[118:119], v[182:183], v[224:225] op_sel_hi:[1,0]
	v_pk_mul_f32 v[116:117], v[8:9], v[116:117]
	v_pk_mul_f32 v[118:119], v[10:11], v[118:119]
	v_cvt_pk_bf16_f32 v228, v116, v117
	v_cvt_pk_bf16_f32 v229, v118, v119
	global_store_dwordx2 v[214:215], v[228:229], off offset:2560
	v_pk_mul_f32 v[120:121], v[184:185], v[224:225] op_sel_hi:[1,0]
	v_pk_mul_f32 v[122:123], v[186:187], v[224:225] op_sel_hi:[1,0]
	v_pk_mul_f32 v[120:121], v[12:13], v[120:121]
	v_pk_mul_f32 v[122:123], v[14:15], v[122:123]
	v_cvt_pk_bf16_f32 v230, v120, v121
	v_cvt_pk_bf16_f32 v231, v122, v123
	global_store_dwordx2 v[214:215], v[230:231], off offset:3072
	v_pk_mul_f32 v[124:125], v[188:189], v[224:225] op_sel_hi:[1,0]
	v_pk_mul_f32 v[126:127], v[190:191], v[224:225] op_sel_hi:[1,0]
	v_pk_mul_f32 v[124:125], v[16:17], v[124:125]
	v_pk_mul_f32 v[126:127], v[18:19], v[126:127]
	v_cvt_pk_bf16_f32 v232, v124, v125
	v_cvt_pk_bf16_f32 v233, v126, v127
	global_store_dwordx2 v[214:215], v[232:233], off offset:3584
	v_mov_b32_e32 v0, v216
	v_cmp_lt_i32_e32 vcc, s97, v0
	s_waitcnt vmcnt(8)
	s_or_b64 s[4:5], vcc, s[4:5]
	s_andn2_b64 exec, exec, s[4:5]
	s_cbranch_execz .LBB0_885
	v_add_u32_e32 v216, s88, v0
	v_cmp_ge_i32_e32 vcc, s97, v216
	s_cbranch_vccz .LnC_nopf1
	v_ashrrev_i32_e32 v209, 31, v216
	v_mov_b32_e32 v208, v216
	v_lshlrev_b64 v[210:211], 12, v[208:209]
	v_lshl_add_u64 v[210:211], v[52:53], 0, v[210:211]
	global_load_dwordx4 v[160:163], v[210:211], off nt
	global_load_dwordx4 v[164:167], v[210:211], off offset:1024 nt
	global_load_dwordx4 v[168:171], v[210:211], off offset:2048 nt
	global_load_dwordx4 v[172:175], v[210:211], off offset:3072 nt
	v_add_co_u32_e32 v210, vcc, 0x1000, v210
	s_nop 1
	v_addc_co_u32_e32 v211, vcc, 0, v211, vcc
	global_load_dwordx4 v[176:179], v[210:211], off nt
	global_load_dwordx4 v[180:183], v[210:211], off offset:1024 nt
	global_load_dwordx4 v[184:187], v[210:211], off offset:2048 nt
	global_load_dwordx4 v[188:191], v[210:211], off offset:3072 nt
; __device__ __forceinline__ unsigned pk2(float lo, float hi) { f32x2_t v = {lo, hi}; bf16x2_t b = __builtin_convertvector(v, bf16x2_t); return __builtin_bit_cast(unsigned, b); }
; __device__ __forceinline__ void rmsnorm_rows_bf16(int swave, const float* xsrc, const bf16_t* add, float* xdst, const float* g, bf16_t* out) {
;     ...
; #pragma unroll
;     for (int u = 0; u < 4; ++u) {
;       s0 += v[u].x * v[u].x + v[u].y * v[u].y + v[u].z * v[u].z + v[u].w * v[u].w;
;       s1 += v[u + 4].x * v[u + 4].x + v[u + 4].y * v[u + 4].y + v[u + 4].z * v[u + 4].z + v[u + 4].w * v[u + 4].w;
;     }
; #pragma unroll
;     for (int o = 32; o > 0; o >>= 1) {
;       s0 += __int_as_float(__builtin_amdgcn_ds_bpermute((lane ^ o) << 2, __float_as_int(s0)));
;       s1 += __int_as_float(__builtin_amdgcn_ds_bpermute((lane ^ o) << 2, __float_as_int(s1)));
;     }
;     const float r0 = rsqrtf(s0 * (1.f / DM) + EPS), r1 = rsqrtf(s1 * (1.f / DM) + EPS);
; #pragma unroll
;     for (int u = 0; u < 8; ++u) {
;       const float r = u < 4 ? r0 : r1; const float4 g4 = gg[u & 3];
;       uint2 o; o.x = pk2(v[u].x * r * g4.x, v[u].y * r * g4.y); o.y = pk2(v[u].z * r * g4.z, v[u].w * r * g4.w);
;       *(uint2*)(out + (size_t)row * DM + (lane + 64 * u) * 4) = o;
;     }
.LnC_nopf1:
	v_ashrrev_i32_e32 v1, 31, v0
	v_lshlrev_b64 v[214:215], 11, v[0:1]
	v_lshl_add_u64 v[214:215], v[54:55], 0, v[214:215]
	v_pk_mul_f32 v[128:129], v[64:65], v[64:65]
	v_pk_mul_f32 v[130:131], v[80:81], v[80:81]
	v_pk_fma_f32 v[128:129], v[66:67], v[66:67], v[128:129]
	v_pk_fma_f32 v[130:131], v[82:83], v[82:83], v[130:131]
	v_pk_fma_f32 v[128:129], v[68:69], v[68:69], v[128:129]
	v_pk_fma_f32 v[130:131], v[84:85], v[84:85], v[130:131]
	v_pk_fma_f32 v[128:129], v[70:71], v[70:71], v[128:129]
	v_pk_fma_f32 v[130:131], v[86:87], v[86:87], v[130:131]
	v_pk_fma_f32 v[128:129], v[72:73], v[72:73], v[128:129]
	v_pk_fma_f32 v[130:131], v[88:89], v[88:89], v[130:131]
	v_pk_fma_f32 v[128:129], v[74:75], v[74:75], v[128:129]
	v_pk_fma_f32 v[130:131], v[90:91], v[90:91], v[130:131]
	v_pk_fma_f32 v[128:129], v[76:77], v[76:77], v[128:129]
	v_pk_fma_f32 v[130:131], v[92:93], v[92:93], v[130:131]
	v_pk_fma_f32 v[128:129], v[78:79], v[78:79], v[128:129]
	v_pk_fma_f32 v[130:131], v[94:95], v[94:95], v[130:131]
	v_add_f32_e32 v218, v128, v129
	v_add_f32_e32 v219, v130, v131
	ds_bpermute_b32 v221, v57, v219
	ds_bpermute_b32 v220, v57, v218
	s_waitcnt lgkmcnt(0)
	v_pk_add_f32 v[218:219], v[218:219], v[220:221]
	ds_bpermute_b32 v221, v58, v219
	ds_bpermute_b32 v220, v58, v218
	s_waitcnt lgkmcnt(0)
	v_pk_add_f32 v[218:219], v[218:219], v[220:221]
	ds_bpermute_b32 v221, v59, v219
	ds_bpermute_b32 v220, v59, v218
	s_waitcnt lgkmcnt(0)
	v_pk_add_f32 v[218:219], v[218:219], v[220:221]
	ds_bpermute_b32 v221, v60, v219
	ds_bpermute_b32 v220, v60, v218
	s_waitcnt lgkmcnt(0)
	v_pk_add_f32 v[218:219], v[218:219], v[220:221]
	ds_bpermute_b32 v221, v61, v219
	ds_bpermute_b32 v220, v61, v218
	s_waitcnt lgkmcnt(0)
	v_pk_add_f32 v[218:219], v[218:219], v[220:221]
	ds_bpermute_b32 v221, v62, v219
	ds_bpermute_b32 v220, v62, v218
	s_waitcnt lgkmcnt(0)
	v_pk_add_f32 v[218:219], v[218:219], v[220:221]
	s_nop 0
	v_pk_fma_f32 v[218:219], v[218:219], s[16:17], v[132:133] op_sel_hi:[1,0,0]
	s_nop 0
	v_mul_f32_e32 v1, 0x4b800000, v218
	v_cmp_gt_f32_e32 vcc, s26, v218
	s_nop 1
	v_cndmask_b32_e32 v1, v218, v1, vcc
	v_rsq_f32_e32 v1, v1
	s_nop 0
	v_mul_f32_e32 v2, 0x45800000, v1
	v_cndmask_b32_e32 v222, v1, v2, vcc
	s_nop 0
	v_mul_f32_e32 v1, 0x4b800000, v219
	v_cmp_gt_f32_e32 vcc, s26, v219
	s_nop 1
	v_cndmask_b32_e32 v1, v219, v1, vcc
	v_rsq_f32_e32 v1, v1
	s_nop 0
	v_mul_f32_e32 v2, 0x45800000, v1
	v_cndmask_b32_e32 v224, v1, v2, vcc
	v_pk_mul_f32 v[112:113], v[64:65], v[222:223] op_sel_hi:[1,0]
	v_pk_mul_f32 v[114:115], v[66:67], v[222:223] op_sel_hi:[1,0]
	v_pk_mul_f32 v[112:113], v[4:5], v[112:113]
	v_pk_mul_f32 v[114:115], v[6:7], v[114:115]
	v_cvt_pk_bf16_f32 v226, v112, v113
	v_cvt_pk_bf16_f32 v227, v114, v115
	global_store_dwordx2 v[214:215], v[226:227], off
	v_pk_mul_f32 v[116:117], v[68:69], v[222:223] op_sel_hi:[1,0]
	v_pk_mul_f32 v[118:119], v[70:71], v[222:223] op_sel_hi:[1,0]
	v_pk_mul_f32 v[116:117], v[8:9], v[116:117]
	v_pk_mul_f32 v[118:119], v[10:11], v[118:119]
	v_cvt_pk_bf16_f32 v228, v116, v117
	v_cvt_pk_bf16_f32 v229, v118, v119
	global_store_dwordx2 v[214:215], v[228:229], off offset:512
	v_pk_mul_f32 v[120:121], v[72:73], v[222:223] op_sel_hi:[1,0]
	v_pk_mul_f32 v[122:123], v[74:75], v[222:223] op_sel_hi:[1,0]
	v_pk_mul_f32 v[120:121], v[12:13], v[120:121]
	v_pk_mul_f32 v[122:123], v[14:15], v[122:123]
	v_cvt_pk_bf16_f32 v230, v120, v121
	v_cvt_pk_bf16_f32 v231, v122, v123
	global_store_dwordx2 v[214:215], v[230:231], off offset:1024
	v_pk_mul_f32 v[124:125], v[76:77], v[222:223] op_sel_hi:[1,0]
	v_pk_mul_f32 v[126:127], v[78:79], v[222:223] op_sel_hi:[1,0]
	v_pk_mul_f32 v[124:125], v[16:17], v[124:125]
	v_pk_mul_f32 v[126:127], v[18:19], v[126:127]
	v_cvt_pk_bf16_f32 v232, v124, v125
	v_cvt_pk_bf16_f32 v233, v126, v127
	global_store_dwordx2 v[214:215], v[232:233], off offset:1536
	v_pk_mul_f32 v[112:113], v[80:81], v[224:225] op_sel_hi:[1,0]
	v_pk_mul_f32 v[114:115], v[82:83], v[224:225] op_sel_hi:[1,0]
	v_pk_mul_f32 v[112:113], v[4:5], v[112:113]
	v_pk_mul_f32 v[114:115], v[6:7], v[114:115]
	v_cvt_pk_bf16_f32 v226, v112, v113
	v_cvt_pk_bf16_f32 v227, v114, v115
	global_store_dwordx2 v[214:215], v[226:227], off offset:2048
	v_pk_mul_f32 v[116:117], v[84:85], v[224:225] op_sel_hi:[1,0]
	v_pk_mul_f32 v[118:119], v[86:87], v[224:225] op_sel_hi:[1,0]
	v_pk_mul_f32 v[116:117], v[8:9], v[116:117]
	v_pk_mul_f32 v[118:119], v[10:11], v[118:119]
	v_cvt_pk_bf16_f32 v228, v116, v117
	v_cvt_pk_bf16_f32 v229, v118, v119
	global_store_dwordx2 v[214:215], v[228:229], off offset:2560
	v_pk_mul_f32 v[120:121], v[88:89], v[224:225] op_sel_hi:[1,0]
	v_pk_mul_f32 v[122:123], v[90:91], v[224:225] op_sel_hi:[1,0]
	v_pk_mul_f32 v[120:121], v[12:13], v[120:121]
	v_pk_mul_f32 v[122:123], v[14:15], v[122:123]
	v_cvt_pk_bf16_f32 v230, v120, v121
	v_cvt_pk_bf16_f32 v231, v122, v123
	global_store_dwordx2 v[214:215], v[230:231], off offset:3072
	v_pk_mul_f32 v[124:125], v[92:93], v[224:225] op_sel_hi:[1,0]
	v_pk_mul_f32 v[126:127], v[94:95], v[224:225] op_sel_hi:[1,0]
	v_pk_mul_f32 v[124:125], v[16:17], v[124:125]
	v_pk_mul_f32 v[126:127], v[18:19], v[126:127]
	v_cvt_pk_bf16_f32 v232, v124, v125
	v_cvt_pk_bf16_f32 v233, v126, v127
	global_store_dwordx2 v[214:215], v[232:233], off offset:3584
	v_mov_b32_e32 v0, v216
	v_cmp_lt_i32_e32 vcc, s97, v0
	s_waitcnt vmcnt(8)
	s_or_b64 s[4:5], vcc, s[4:5]
	s_andn2_b64 exec, exec, s[4:5]
	s_cbranch_execnz .LnC_loop
